# first K-loop trip of each GEMM unit peeled with C=0 (no per-unit accumulator zeroing); 4-phase K-loop also in the in-proj GEMM
# speedup vs baseline: 1.0123x; 1.0123x over previous
.LBB0_98:
	v_mov_b64_e32 v[2:3], 0x5ac
	s_ashr_i32 s9, s8, 31
	v_cmp_lt_i64_e32 vcc, s[10:11], v[2:3]
	s_lshl_b64 s[10:11], s[8:9], 19
	s_add_u32 s10, s54, s10
	s_addc_u32 s11, s55, s11
	s_and_b64 s[12:13], vcc, exec
	s_cselect_b32 s9, s11, s15
	s_cselect_b32 s40, s10, s14
	s_ashr_i32 s7, s6, 31
	s_lshl_b64 s[12:13], s[6:7], 19
	s_add_u32 s12, s23, s12
	s_addc_u32 s13, s24, s13
	s_and_b64 s[18:19], vcc, exec
	s_cselect_b32 s7, s13, s17
	s_cselect_b32 s41, s12, s16
	s_add_u32 s14, s14, 0x40080
	s_addc_u32 s15, s15, 0
	s_add_u32 s42, s16, 0x100
	s_addc_u32 s43, s17, 0
	s_mov_b32 s44, -2
	s_add_u32 s16, s14, 0xfffc0080
	s_addc_u32 s17, s15, -1
	s_add_i32 s45, 0, 0x10000
	v_add_u32_e32 v249, s45, v139
	ds_read_b128 v[142:145], v249
	ds_read_b128 v[146:149], v249 offset:1024
	ds_read_b128 v[150:153], v249 offset:2048
	ds_read_b128 v[154:157], v249 offset:3072
	s_cmp_eq_u32 s44, 12
	s_cselect_b32 s19, s9, s17
	s_cselect_b32 s18, s40, s16
	s_cselect_b32 s17, s7, s43
	s_cselect_b32 s16, s41, s42
	s_add_i32 s48, 0, 0x14000
	ds_read_b128 v[204:207], v249 offset:16384
	ds_read_b128 v[208:211], v249 offset:17408
	ds_read_b128 v[212:215], v249 offset:18432
	ds_read_b128 v[216:219], v249 offset:19456
	s_add_i32 m0, s26, 0xc000
	ds_read_b128 v[158:161], v140
	ds_read_b128 v[162:165], v140 offset:1024
	ds_read_b128 v[166:169], v140 offset:2048
	ds_read_b128 v[170:173], v140 offset:3072
	ds_read_b128 v[174:177], v140 offset:4096
	ds_read_b128 v[178:181], v140 offset:5120
	ds_read_b128 v[182:185], v140 offset:6144
	ds_read_b128 v[186:189], v140 offset:7168
	global_load_lds_dwordx4 v134, s[14:15]
	s_add_i32 m0, s26, 0xe000
	s_nop 0
	global_load_lds_dwordx4 v136, s[14:15]
	s_waitcnt vmcnt(8) lgkmcnt(0)
	s_barrier
	s_setprio 1
	v_mfma_f32_16x16x32_bf16 v[126:129], v[142:145], v[158:161], 0
	v_mfma_f32_16x16x32_bf16 v[122:125], v[150:153], v[158:161], 0
	v_mfma_f32_16x16x32_bf16 v[110:113], v[142:145], v[166:169], 0
	v_mfma_f32_16x16x32_bf16 v[106:109], v[150:153], v[166:169], 0
	v_mfma_f32_16x16x32_bf16 v[94:97], v[142:145], v[174:177], 0
	v_mfma_f32_16x16x32_bf16 v[90:93], v[150:153], v[174:177], 0
	v_mfma_f32_16x16x32_bf16 v[78:81], v[142:145], v[182:185], 0
	v_mfma_f32_16x16x32_bf16 v[74:77], v[150:153], v[182:185], 0
	v_mfma_f32_16x16x32_bf16 v[126:129], v[146:149], v[162:165], v[126:129]
	v_mfma_f32_16x16x32_bf16 v[122:125], v[154:157], v[162:165], v[122:125]
	v_mfma_f32_16x16x32_bf16 v[110:113], v[146:149], v[170:173], v[110:113]
	v_mfma_f32_16x16x32_bf16 v[106:109], v[154:157], v[170:173], v[106:109]
	v_mfma_f32_16x16x32_bf16 v[94:97], v[146:149], v[178:181], v[94:97]
	v_mfma_f32_16x16x32_bf16 v[90:93], v[154:157], v[178:181], v[90:93]
	v_mfma_f32_16x16x32_bf16 v[78:81], v[146:149], v[186:189], v[78:81]
	v_mfma_f32_16x16x32_bf16 v[74:77], v[154:157], v[186:189], v[74:77]
	v_mfma_f32_16x16x32_bf16 v[118:121], v[204:207], v[158:161], 0
	v_mfma_f32_16x16x32_bf16 v[114:117], v[212:215], v[158:161], 0
	v_mfma_f32_16x16x32_bf16 v[102:105], v[204:207], v[166:169], 0
	v_mfma_f32_16x16x32_bf16 v[98:101], v[212:215], v[166:169], 0
	v_mfma_f32_16x16x32_bf16 v[86:89], v[204:207], v[174:177], 0
	v_mfma_f32_16x16x32_bf16 v[82:85], v[212:215], v[174:177], 0
	v_mfma_f32_16x16x32_bf16 v[70:73], v[204:207], v[182:185], 0
	v_mfma_f32_16x16x32_bf16 v[66:69], v[212:215], v[182:185], 0
	v_mfma_f32_16x16x32_bf16 v[118:121], v[208:211], v[162:165], v[118:121]
	v_mfma_f32_16x16x32_bf16 v[114:117], v[216:219], v[162:165], v[114:117]
	v_mfma_f32_16x16x32_bf16 v[102:105], v[208:211], v[170:173], v[102:105]
	v_mfma_f32_16x16x32_bf16 v[98:101], v[216:219], v[170:173], v[98:101]
	v_mfma_f32_16x16x32_bf16 v[86:89], v[208:211], v[178:181], v[86:89]
	v_mfma_f32_16x16x32_bf16 v[82:85], v[216:219], v[178:181], v[82:85]
	v_mfma_f32_16x16x32_bf16 v[70:73], v[208:211], v[186:189], v[70:73]
	v_mfma_f32_16x16x32_bf16 v[66:69], v[216:219], v[186:189], v[66:69]
	s_setprio 0
	s_barrier
	ds_read_b128 v[158:161], v140 offset:16384
	ds_read_b128 v[162:165], v140 offset:17408
	ds_read_b128 v[166:169], v140 offset:18432
	ds_read_b128 v[170:173], v140 offset:19456
	ds_read_b128 v[174:177], v140 offset:20480
	ds_read_b128 v[178:181], v140 offset:21504
	ds_read_b128 v[182:185], v140 offset:22528
	ds_read_b128 v[186:189], v140 offset:23552
	s_add_i32 s45, s45, s25
	s_mov_b32 m0, s45
	s_nop 0
	global_load_lds_dwordx4 v132, s[16:17]
	s_add_i32 m0, s45, 0x2000
	s_nop 0
	global_load_lds_dwordx4 v130, s[16:17]
	s_mov_b32 m0, s26
	s_add_u32 s98, s18, 0x80
	s_addc_u32 s99, s19, 0
	global_load_lds_dwordx4 v132, s[18:19]
	s_mov_b32 m0, s27
	s_nop 0
	global_load_lds_dwordx4 v130, s[18:19]
	s_add_u32 s46, s16, 0x40000
	s_addc_u32 s47, s17, 0
	s_add_i32 s45, s48, s25
	s_mov_b32 m0, s45
	s_nop 0
	global_load_lds_dwordx4 v132, s[46:47]
	s_add_i32 m0, s45, 0x2000
	s_nop 0
	global_load_lds_dwordx4 v130, s[46:47]
	s_waitcnt vmcnt(8) lgkmcnt(0)
	s_barrier
	s_setprio 1
	v_mfma_f32_16x16x32_bf16 v[62:65], v[142:145], v[158:161], 0
	v_mfma_f32_16x16x32_bf16 v[58:61], v[150:153], v[158:161], 0
	v_mfma_f32_16x16x32_bf16 v[46:49], v[142:145], v[166:169], 0
	v_mfma_f32_16x16x32_bf16 v[42:45], v[150:153], v[166:169], 0
	v_mfma_f32_16x16x32_bf16 v[30:33], v[142:145], v[174:177], 0
	v_mfma_f32_16x16x32_bf16 v[26:29], v[150:153], v[174:177], 0
	v_mfma_f32_16x16x32_bf16 v[14:17], v[142:145], v[182:185], 0
	v_mfma_f32_16x16x32_bf16 v[10:13], v[150:153], v[182:185], 0
	v_mfma_f32_16x16x32_bf16 v[62:65], v[146:149], v[162:165], v[62:65]
	v_mfma_f32_16x16x32_bf16 v[58:61], v[154:157], v[162:165], v[58:61]
	v_mfma_f32_16x16x32_bf16 v[46:49], v[146:149], v[170:173], v[46:49]
	v_mfma_f32_16x16x32_bf16 v[42:45], v[154:157], v[170:173], v[42:45]
	v_mfma_f32_16x16x32_bf16 v[30:33], v[146:149], v[178:181], v[30:33]
	v_mfma_f32_16x16x32_bf16 v[26:29], v[154:157], v[178:181], v[26:29]
	v_mfma_f32_16x16x32_bf16 v[14:17], v[146:149], v[186:189], v[14:17]
	v_mfma_f32_16x16x32_bf16 v[10:13], v[154:157], v[186:189], v[10:13]
	v_mfma_f32_16x16x32_bf16 v[54:57], v[204:207], v[158:161], 0
	v_mfma_f32_16x16x32_bf16 v[50:53], v[212:215], v[158:161], 0
	v_mfma_f32_16x16x32_bf16 v[38:41], v[204:207], v[166:169], 0
	v_mfma_f32_16x16x32_bf16 v[34:37], v[212:215], v[166:169], 0
	v_mfma_f32_16x16x32_bf16 v[22:25], v[204:207], v[174:177], 0
	v_mfma_f32_16x16x32_bf16 v[18:21], v[212:215], v[174:177], 0
	v_mfma_f32_16x16x32_bf16 v[6:9], v[204:207], v[182:185], 0
	v_mfma_f32_16x16x32_bf16 v[2:5], v[212:215], v[182:185], 0
	v_mfma_f32_16x16x32_bf16 v[54:57], v[208:211], v[162:165], v[54:57]
	v_mfma_f32_16x16x32_bf16 v[50:53], v[216:219], v[162:165], v[50:53]
	v_mfma_f32_16x16x32_bf16 v[38:41], v[208:211], v[170:173], v[38:41]
	v_mfma_f32_16x16x32_bf16 v[34:37], v[216:219], v[170:173], v[34:37]
	v_mfma_f32_16x16x32_bf16 v[22:25], v[208:211], v[178:181], v[22:25]
	v_mfma_f32_16x16x32_bf16 v[18:21], v[216:219], v[178:181], v[18:21]
	v_mfma_f32_16x16x32_bf16 v[6:9], v[208:211], v[186:189], v[6:9]
	v_mfma_f32_16x16x32_bf16 v[2:5], v[216:219], v[186:189], v[2:5]
	s_setprio 0
	s_barrier
	s_add_i32 s45, 0, 0x18000
	ds_read_b128 v[142:145], v249 offset:32768
	ds_read_b128 v[146:149], v249 offset:33792
	ds_read_b128 v[150:153], v249 offset:34816
	ds_read_b128 v[154:157], v249 offset:35840
	s_add_u32 s18, s18, 0x40000
	s_addc_u32 s19, s19, 0
	s_mov_b32 m0, s28
	ds_read_b128 v[158:161], v140 offset:32768
	ds_read_b128 v[162:165], v140 offset:33792
	ds_read_b128 v[166:169], v140 offset:34816
	ds_read_b128 v[170:173], v140 offset:35840
	ds_read_b128 v[174:177], v140 offset:36864
	ds_read_b128 v[178:181], v140 offset:37888
	ds_read_b128 v[182:185], v140 offset:38912
	ds_read_b128 v[186:189], v140 offset:39936
	global_load_lds_dwordx4 v132, s[18:19]
	s_mov_b32 m0, s29
	s_nop 0
	global_load_lds_dwordx4 v130, s[18:19]
	s_add_i32 s18, 0, 0x1c000
	ds_read_b128 v[204:207], v249 offset:49152
	ds_read_b128 v[208:211], v249 offset:50176
	ds_read_b128 v[212:215], v249 offset:51200
	ds_read_b128 v[216:219], v249 offset:52224
	s_waitcnt vmcnt(8) lgkmcnt(0)
	s_barrier
	s_setprio 1
	v_mfma_f32_16x16x32_bf16 v[126:129], v[142:145], v[158:161], v[126:129]
	v_mfma_f32_16x16x32_bf16 v[122:125], v[150:153], v[158:161], v[122:125]
	v_mfma_f32_16x16x32_bf16 v[110:113], v[142:145], v[166:169], v[110:113]
	v_mfma_f32_16x16x32_bf16 v[106:109], v[150:153], v[166:169], v[106:109]
	v_mfma_f32_16x16x32_bf16 v[94:97], v[142:145], v[174:177], v[94:97]
	v_mfma_f32_16x16x32_bf16 v[90:93], v[150:153], v[174:177], v[90:93]
	v_mfma_f32_16x16x32_bf16 v[78:81], v[142:145], v[182:185], v[78:81]
	v_mfma_f32_16x16x32_bf16 v[74:77], v[150:153], v[182:185], v[74:77]
	v_mfma_f32_16x16x32_bf16 v[126:129], v[146:149], v[162:165], v[126:129]
	v_mfma_f32_16x16x32_bf16 v[122:125], v[154:157], v[162:165], v[122:125]
	v_mfma_f32_16x16x32_bf16 v[110:113], v[146:149], v[170:173], v[110:113]
	v_mfma_f32_16x16x32_bf16 v[106:109], v[154:157], v[170:173], v[106:109]
	v_mfma_f32_16x16x32_bf16 v[94:97], v[146:149], v[178:181], v[94:97]
	v_mfma_f32_16x16x32_bf16 v[90:93], v[154:157], v[178:181], v[90:93]
	v_mfma_f32_16x16x32_bf16 v[78:81], v[146:149], v[186:189], v[78:81]
	v_mfma_f32_16x16x32_bf16 v[74:77], v[154:157], v[186:189], v[74:77]
	v_mfma_f32_16x16x32_bf16 v[118:121], v[204:207], v[158:161], v[118:121]
	v_mfma_f32_16x16x32_bf16 v[114:117], v[212:215], v[158:161], v[114:117]
	v_mfma_f32_16x16x32_bf16 v[102:105], v[204:207], v[166:169], v[102:105]
	v_mfma_f32_16x16x32_bf16 v[98:101], v[212:215], v[166:169], v[98:101]
	v_mfma_f32_16x16x32_bf16 v[86:89], v[204:207], v[174:177], v[86:89]
	v_mfma_f32_16x16x32_bf16 v[82:85], v[212:215], v[174:177], v[82:85]
	v_mfma_f32_16x16x32_bf16 v[70:73], v[204:207], v[182:185], v[70:73]
	v_mfma_f32_16x16x32_bf16 v[66:69], v[212:215], v[182:185], v[66:69]
	v_mfma_f32_16x16x32_bf16 v[118:121], v[208:211], v[162:165], v[118:121]
	v_mfma_f32_16x16x32_bf16 v[114:117], v[216:219], v[162:165], v[114:117]
	v_mfma_f32_16x16x32_bf16 v[102:105], v[208:211], v[170:173], v[102:105]
	v_mfma_f32_16x16x32_bf16 v[98:101], v[216:219], v[170:173], v[98:101]
	v_mfma_f32_16x16x32_bf16 v[86:89], v[208:211], v[178:181], v[86:89]
	v_mfma_f32_16x16x32_bf16 v[82:85], v[216:219], v[178:181], v[82:85]
	v_mfma_f32_16x16x32_bf16 v[70:73], v[208:211], v[186:189], v[70:73]
	v_mfma_f32_16x16x32_bf16 v[66:69], v[216:219], v[186:189], v[66:69]
	s_setprio 0
	s_barrier
	ds_read_b128 v[158:161], v140 offset:49152
	ds_read_b128 v[162:165], v140 offset:50176
	ds_read_b128 v[166:169], v140 offset:51200
	ds_read_b128 v[170:173], v140 offset:52224
	ds_read_b128 v[174:177], v140 offset:53248
	ds_read_b128 v[178:181], v140 offset:54272
	ds_read_b128 v[182:185], v140 offset:55296
	ds_read_b128 v[186:189], v140 offset:56320
	s_add_i32 s19, s45, s25
	s_mov_b32 m0, s19
	s_add_u32 vcc_lo, s16, 0x80
	s_addc_u32 vcc_hi, s17, 0
	global_load_lds_dwordx4 v132, vcc
	s_add_i32 m0, s19, 0x2000
	s_nop 0
	global_load_lds_dwordx4 v130, vcc
	s_mov_b32 m0, s30
	s_nop 0
	global_load_lds_dwordx4 v132, s[98:99]
	s_mov_b32 m0, s31
	s_nop 0
	global_load_lds_dwordx4 v130, s[98:99]
	s_add_u32 s16, s16, 0x40080
	s_addc_u32 s17, s17, 0
	s_add_i32 s18, s18, s25
	s_mov_b32 m0, s18
	s_nop 0
	global_load_lds_dwordx4 v132, s[16:17]
	s_add_i32 m0, s18, 0x2000
	s_nop 0
	global_load_lds_dwordx4 v130, s[16:17]
	s_waitcnt vmcnt(8) lgkmcnt(0)
	s_barrier
	s_setprio 1
	v_mfma_f32_16x16x32_bf16 v[62:65], v[142:145], v[158:161], v[62:65]
	v_mfma_f32_16x16x32_bf16 v[58:61], v[150:153], v[158:161], v[58:61]
	v_mfma_f32_16x16x32_bf16 v[46:49], v[142:145], v[166:169], v[46:49]
	v_mfma_f32_16x16x32_bf16 v[42:45], v[150:153], v[166:169], v[42:45]
	v_mfma_f32_16x16x32_bf16 v[30:33], v[142:145], v[174:177], v[30:33]
	v_mfma_f32_16x16x32_bf16 v[26:29], v[150:153], v[174:177], v[26:29]
	v_mfma_f32_16x16x32_bf16 v[14:17], v[142:145], v[182:185], v[14:17]
	v_mfma_f32_16x16x32_bf16 v[10:13], v[150:153], v[182:185], v[10:13]
	v_mfma_f32_16x16x32_bf16 v[62:65], v[146:149], v[162:165], v[62:65]
	v_mfma_f32_16x16x32_bf16 v[58:61], v[154:157], v[162:165], v[58:61]
	v_mfma_f32_16x16x32_bf16 v[46:49], v[146:149], v[170:173], v[46:49]
	v_mfma_f32_16x16x32_bf16 v[42:45], v[154:157], v[170:173], v[42:45]
	v_mfma_f32_16x16x32_bf16 v[30:33], v[146:149], v[178:181], v[30:33]
	v_mfma_f32_16x16x32_bf16 v[26:29], v[154:157], v[178:181], v[26:29]
	v_mfma_f32_16x16x32_bf16 v[14:17], v[146:149], v[186:189], v[14:17]
	v_mfma_f32_16x16x32_bf16 v[10:13], v[154:157], v[186:189], v[10:13]
	v_mfma_f32_16x16x32_bf16 v[54:57], v[204:207], v[158:161], v[54:57]
	v_mfma_f32_16x16x32_bf16 v[50:53], v[212:215], v[158:161], v[50:53]
	v_mfma_f32_16x16x32_bf16 v[38:41], v[204:207], v[166:169], v[38:41]
	v_mfma_f32_16x16x32_bf16 v[34:37], v[212:215], v[166:169], v[34:37]
	v_mfma_f32_16x16x32_bf16 v[22:25], v[204:207], v[174:177], v[22:25]
	v_mfma_f32_16x16x32_bf16 v[18:21], v[212:215], v[174:177], v[18:21]
	v_mfma_f32_16x16x32_bf16 v[6:9], v[204:207], v[182:185], v[6:9]
	v_mfma_f32_16x16x32_bf16 v[2:5], v[212:215], v[182:185], v[2:5]
	v_mfma_f32_16x16x32_bf16 v[54:57], v[208:211], v[162:165], v[54:57]
	v_mfma_f32_16x16x32_bf16 v[50:53], v[216:219], v[162:165], v[50:53]
	v_mfma_f32_16x16x32_bf16 v[38:41], v[208:211], v[170:173], v[38:41]
	v_mfma_f32_16x16x32_bf16 v[34:37], v[216:219], v[170:173], v[34:37]
	v_mfma_f32_16x16x32_bf16 v[22:25], v[208:211], v[178:181], v[22:25]
	v_mfma_f32_16x16x32_bf16 v[18:21], v[216:219], v[178:181], v[18:21]
	v_mfma_f32_16x16x32_bf16 v[6:9], v[208:211], v[186:189], v[6:9]
	v_mfma_f32_16x16x32_bf16 v[2:5], v[216:219], v[186:189], v[2:5]
	s_setprio 0
	s_add_i32 s44, s44, 2
	s_add_u32 s14, s14, 0x100
	s_addc_u32 s15, s15, 0
	s_add_u32 s42, s42, 0x100
	s_addc_u32 s43, s43, 0
	s_cmp_gt_u32 s44, 13
	s_barrier

.LBB0_277:
	v_mov_b64_e32 v[2:3], 0x100
	s_ashr_i32 s9, s8, 31
	v_cmp_lt_i64_e32 vcc, s[10:11], v[2:3]
	s_lshl_b64 s[10:11], s[8:9], 19
	s_add_u32 s10, s0, s10
	s_addc_u32 s11, s1, s11
	s_and_b64 s[12:13], vcc, exec
	s_cselect_b32 s9, s11, s15
	s_cselect_b32 s36, s10, s14
	s_ashr_i32 s7, s6, 31
	s_lshl_b64 s[12:13], s[6:7], 19
	s_add_u32 s12, s2, s12
	s_addc_u32 s13, s3, s13
	s_and_b64 s[18:19], vcc, exec
	s_cselect_b32 s7, s13, s17
	s_cselect_b32 s37, s12, s16
	s_add_u32 s14, s14, 0x40080
	s_addc_u32 s15, s15, 0
	s_add_u32 s44, s16, 0x100
	s_addc_u32 s45, s17, 0
	s_mov_b32 s46, -2
	s_add_u32 s16, s14, 0xfffc0080
	s_addc_u32 s17, s15, -1
	s_add_i32 s47, 0, 0x10000
	v_add_u32_e32 v249, s47, v203
	ds_read_b128 v[118:121], v249
	ds_read_b128 v[122:125], v249 offset:1024
	ds_read_b128 v[130:133], v249 offset:2048
	ds_read_b128 v[134:137], v249 offset:3072
	s_cmp_eq_u32 s46, 12
	s_cselect_b32 s19, s9, s17
	s_cselect_b32 s18, s36, s16
	s_cselect_b32 s17, s7, s45
	s_cselect_b32 s16, s37, s44
	s_add_i32 m0, s23, 0xc000
	ds_read_b128 v[138:141], v220
	ds_read_b128 v[146:149], v220 offset:1024
	ds_read_b128 v[154:157], v220 offset:2048
	ds_read_b128 v[158:161], v220 offset:3072
	ds_read_b128 v[162:165], v220 offset:4096
	ds_read_b128 v[166:169], v220 offset:5120
	ds_read_b128 v[170:173], v220 offset:6144
	ds_read_b128 v[174:177], v220 offset:7168
	global_load_lds_dwordx4 v212, s[14:15]
	s_add_i32 m0, s23, 0xe000
	s_nop 0
	global_load_lds_dwordx4 v214, s[14:15]
	s_waitcnt lgkmcnt(8)
	s_barrier
	s_waitcnt lgkmcnt(0)
	s_setprio 1
	s_waitcnt lgkmcnt(0)
	v_mfma_f32_16x16x32_bf16 v[150:153], v[118:121], v[138:141], 0
	v_mfma_f32_16x16x32_bf16 v[142:145], v[130:133], v[138:141], 0
	v_mfma_f32_16x16x32_bf16 v[110:113], v[118:121], v[154:157], 0
	v_mfma_f32_16x16x32_bf16 v[106:109], v[130:133], v[154:157], 0
	v_mfma_f32_16x16x32_bf16 v[94:97], v[118:121], v[162:165], 0
	v_mfma_f32_16x16x32_bf16 v[90:93], v[130:133], v[162:165], 0
	v_mfma_f32_16x16x32_bf16 v[78:81], v[118:121], v[170:173], 0
	v_mfma_f32_16x16x32_bf16 v[74:77], v[130:133], v[170:173], 0
	v_mfma_f32_16x16x32_bf16 v[150:153], v[122:125], v[146:149], v[150:153]
	v_mfma_f32_16x16x32_bf16 v[142:145], v[134:137], v[146:149], v[142:145]
	v_mfma_f32_16x16x32_bf16 v[110:113], v[122:125], v[158:161], v[110:113]
	v_mfma_f32_16x16x32_bf16 v[106:109], v[134:137], v[158:161], v[106:109]
	v_mfma_f32_16x16x32_bf16 v[94:97], v[122:125], v[166:169], v[94:97]
	v_mfma_f32_16x16x32_bf16 v[90:93], v[134:137], v[166:169], v[90:93]
	v_mfma_f32_16x16x32_bf16 v[78:81], v[122:125], v[174:177], v[78:81]
	v_mfma_f32_16x16x32_bf16 v[74:77], v[134:137], v[174:177], v[74:77]
	s_setprio 0
	s_barrier
	s_add_i32 s50, 0, 0x14000
	s_add_i32 s47, s47, s22
	ds_read_b128 v[178:181], v249 offset:16384
	ds_read_b128 v[182:185], v249 offset:17408
	ds_read_b128 v[186:189], v249 offset:18432
	ds_read_b128 v[216:219], v249 offset:19456
	s_mov_b32 m0, s47
	s_nop 0
	global_load_lds_dwordx4 v208, s[16:17]
	s_add_i32 m0, s47, 0x2000
	s_nop 0
	global_load_lds_dwordx4 v204, s[16:17]
	s_barrier
	s_waitcnt lgkmcnt(0)
	s_setprio 1
	s_waitcnt lgkmcnt(0)
	v_mfma_f32_16x16x32_bf16 v[126:129], v[178:181], v[138:141], 0
	v_mfma_f32_16x16x32_bf16 v[114:117], v[186:189], v[138:141], 0
	v_mfma_f32_16x16x32_bf16 v[102:105], v[178:181], v[154:157], 0
	v_mfma_f32_16x16x32_bf16 v[98:101], v[186:189], v[154:157], 0
	v_mfma_f32_16x16x32_bf16 v[86:89], v[178:181], v[162:165], 0
	v_mfma_f32_16x16x32_bf16 v[82:85], v[186:189], v[162:165], 0
	v_mfma_f32_16x16x32_bf16 v[70:73], v[178:181], v[170:173], 0
	v_mfma_f32_16x16x32_bf16 v[66:69], v[186:189], v[170:173], 0
	v_mfma_f32_16x16x32_bf16 v[126:129], v[182:185], v[146:149], v[126:129]
	v_mfma_f32_16x16x32_bf16 v[114:117], v[216:219], v[146:149], v[114:117]
	v_mfma_f32_16x16x32_bf16 v[102:105], v[182:185], v[158:161], v[102:105]
	v_mfma_f32_16x16x32_bf16 v[98:101], v[216:219], v[158:161], v[98:101]
	v_mfma_f32_16x16x32_bf16 v[86:89], v[182:185], v[166:169], v[86:89]
	v_mfma_f32_16x16x32_bf16 v[82:85], v[216:219], v[166:169], v[82:85]
	v_mfma_f32_16x16x32_bf16 v[70:73], v[182:185], v[174:177], v[70:73]
	v_mfma_f32_16x16x32_bf16 v[66:69], v[216:219], v[174:177], v[66:69]
	s_setprio 0
	s_mov_b32 m0, s23
	s_add_u32 s98, s18, 0x80
	s_addc_u32 s99, s19, 0
	s_barrier
	ds_read_b128 v[138:141], v220 offset:16384
	ds_read_b128 v[146:149], v220 offset:17408
	ds_read_b128 v[154:157], v220 offset:18432
	ds_read_b128 v[158:161], v220 offset:19456
	ds_read_b128 v[162:165], v220 offset:20480
	ds_read_b128 v[166:169], v220 offset:21504
	ds_read_b128 v[170:173], v220 offset:22528
	ds_read_b128 v[174:177], v220 offset:23552
	global_load_lds_dwordx4 v210, s[18:19]
	s_mov_b32 m0, s24
	s_nop 0
	global_load_lds_dwordx4 v206, s[18:19]
	s_barrier
	s_waitcnt lgkmcnt(0)
	s_setprio 1
	s_waitcnt lgkmcnt(0)
	v_mfma_f32_16x16x32_bf16 v[62:65], v[118:121], v[138:141], 0
	v_mfma_f32_16x16x32_bf16 v[58:61], v[130:133], v[138:141], 0
	v_mfma_f32_16x16x32_bf16 v[46:49], v[118:121], v[154:157], 0
	v_mfma_f32_16x16x32_bf16 v[42:45], v[130:133], v[154:157], 0
	v_mfma_f32_16x16x32_bf16 v[30:33], v[118:121], v[162:165], 0
	v_mfma_f32_16x16x32_bf16 v[26:29], v[130:133], v[162:165], 0
	v_mfma_f32_16x16x32_bf16 v[14:17], v[118:121], v[170:173], 0
	v_mfma_f32_16x16x32_bf16 v[10:13], v[130:133], v[170:173], 0
	v_mfma_f32_16x16x32_bf16 v[62:65], v[122:125], v[146:149], v[62:65]
	v_mfma_f32_16x16x32_bf16 v[58:61], v[134:137], v[146:149], v[58:61]
	v_mfma_f32_16x16x32_bf16 v[46:49], v[122:125], v[158:161], v[46:49]
	v_mfma_f32_16x16x32_bf16 v[42:45], v[134:137], v[158:161], v[42:45]
	v_mfma_f32_16x16x32_bf16 v[30:33], v[122:125], v[166:169], v[30:33]
	v_mfma_f32_16x16x32_bf16 v[26:29], v[134:137], v[166:169], v[26:29]
	v_mfma_f32_16x16x32_bf16 v[14:17], v[122:125], v[174:177], v[14:17]
	v_mfma_f32_16x16x32_bf16 v[10:13], v[134:137], v[174:177], v[10:13]
	s_setprio 0
	s_barrier
	s_add_u32 s48, s16, 0x40000
	s_addc_u32 s49, s17, 0
	s_add_i32 s47, s50, s22
	s_mov_b32 m0, s47
	s_nop 0
	global_load_lds_dwordx4 v208, s[48:49]
	s_add_i32 m0, s47, 0x2000
	s_nop 0
	global_load_lds_dwordx4 v204, s[48:49]
	s_waitcnt vmcnt(6)
	s_barrier
	s_setprio 1
	v_mfma_f32_16x16x32_bf16 v[54:57], v[178:181], v[138:141], 0
	v_mfma_f32_16x16x32_bf16 v[50:53], v[186:189], v[138:141], 0
	v_mfma_f32_16x16x32_bf16 v[38:41], v[178:181], v[154:157], 0
	v_mfma_f32_16x16x32_bf16 v[34:37], v[186:189], v[154:157], 0
	v_mfma_f32_16x16x32_bf16 v[22:25], v[178:181], v[162:165], 0
	v_mfma_f32_16x16x32_bf16 v[18:21], v[186:189], v[162:165], 0
	v_mfma_f32_16x16x32_bf16 v[6:9], v[178:181], v[170:173], 0
	v_mfma_f32_16x16x32_bf16 v[2:5], v[186:189], v[170:173], 0
	v_mfma_f32_16x16x32_bf16 v[54:57], v[182:185], v[146:149], v[54:57]
	v_mfma_f32_16x16x32_bf16 v[50:53], v[216:219], v[146:149], v[50:53]
	v_mfma_f32_16x16x32_bf16 v[38:41], v[182:185], v[158:161], v[38:41]
	v_mfma_f32_16x16x32_bf16 v[34:37], v[216:219], v[158:161], v[34:37]
	v_mfma_f32_16x16x32_bf16 v[22:25], v[182:185], v[166:169], v[22:25]
	v_mfma_f32_16x16x32_bf16 v[18:21], v[216:219], v[166:169], v[18:21]
	v_mfma_f32_16x16x32_bf16 v[6:9], v[182:185], v[174:177], v[6:9]
	v_mfma_f32_16x16x32_bf16 v[2:5], v[216:219], v[174:177], v[2:5]
	s_setprio 0
	s_add_i32 s47, 0, 0x18000
	s_barrier
	ds_read_b128 v[118:121], v249 offset:32768
	ds_read_b128 v[122:125], v249 offset:33792
	ds_read_b128 v[130:133], v249 offset:34816
	ds_read_b128 v[134:137], v249 offset:35840
	s_add_u32 s18, s18, 0x40000
	s_addc_u32 s19, s19, 0
	s_mov_b32 m0, s25
	ds_read_b128 v[138:141], v220 offset:32768
	ds_read_b128 v[146:149], v220 offset:33792
	ds_read_b128 v[154:157], v220 offset:34816
	ds_read_b128 v[158:161], v220 offset:35840
	ds_read_b128 v[162:165], v220 offset:36864
	ds_read_b128 v[166:169], v220 offset:37888
	ds_read_b128 v[170:173], v220 offset:38912
	ds_read_b128 v[174:177], v220 offset:39936
	global_load_lds_dwordx4 v210, s[18:19]
	s_mov_b32 m0, s26
	s_nop 0
	global_load_lds_dwordx4 v206, s[18:19]
	s_waitcnt lgkmcnt(8)
	s_barrier
	s_waitcnt lgkmcnt(0)
	s_setprio 1
	s_waitcnt lgkmcnt(0)
	v_mfma_f32_16x16x32_bf16 v[150:153], v[118:121], v[138:141], v[150:153]
	v_mfma_f32_16x16x32_bf16 v[142:145], v[130:133], v[138:141], v[142:145]
	v_mfma_f32_16x16x32_bf16 v[110:113], v[118:121], v[154:157], v[110:113]
	v_mfma_f32_16x16x32_bf16 v[106:109], v[130:133], v[154:157], v[106:109]
	v_mfma_f32_16x16x32_bf16 v[94:97], v[118:121], v[162:165], v[94:97]
	v_mfma_f32_16x16x32_bf16 v[90:93], v[130:133], v[162:165], v[90:93]
	v_mfma_f32_16x16x32_bf16 v[78:81], v[118:121], v[170:173], v[78:81]
	v_mfma_f32_16x16x32_bf16 v[74:77], v[130:133], v[170:173], v[74:77]
	v_mfma_f32_16x16x32_bf16 v[150:153], v[122:125], v[146:149], v[150:153]
	v_mfma_f32_16x16x32_bf16 v[142:145], v[134:137], v[146:149], v[142:145]
	v_mfma_f32_16x16x32_bf16 v[110:113], v[122:125], v[158:161], v[110:113]
	v_mfma_f32_16x16x32_bf16 v[106:109], v[134:137], v[158:161], v[106:109]
	v_mfma_f32_16x16x32_bf16 v[94:97], v[122:125], v[166:169], v[94:97]
	v_mfma_f32_16x16x32_bf16 v[90:93], v[134:137], v[166:169], v[90:93]
	v_mfma_f32_16x16x32_bf16 v[78:81], v[122:125], v[174:177], v[78:81]
	v_mfma_f32_16x16x32_bf16 v[74:77], v[134:137], v[174:177], v[74:77]
	s_setprio 0
	s_barrier
	s_add_i32 s18, 0, 0x1c000
	s_add_i32 s19, s47, s22
	s_add_u32 vcc_lo, s16, 0x80
	s_addc_u32 vcc_hi, s17, 0
	s_mov_b32 m0, s19
	ds_read_b128 v[178:181], v249 offset:49152
	ds_read_b128 v[182:185], v249 offset:50176
	ds_read_b128 v[186:189], v249 offset:51200
	ds_read_b128 v[216:219], v249 offset:52224
	global_load_lds_dwordx4 v208, vcc
	s_add_i32 m0, s19, 0x2000
	s_nop 0
	global_load_lds_dwordx4 v204, vcc
	s_barrier
	s_waitcnt lgkmcnt(0)
	s_setprio 1
	s_waitcnt lgkmcnt(0)
	v_mfma_f32_16x16x32_bf16 v[126:129], v[178:181], v[138:141], v[126:129]
	v_mfma_f32_16x16x32_bf16 v[114:117], v[186:189], v[138:141], v[114:117]
	v_mfma_f32_16x16x32_bf16 v[102:105], v[178:181], v[154:157], v[102:105]
	v_mfma_f32_16x16x32_bf16 v[98:101], v[186:189], v[154:157], v[98:101]
	v_mfma_f32_16x16x32_bf16 v[86:89], v[178:181], v[162:165], v[86:89]
	v_mfma_f32_16x16x32_bf16 v[82:85], v[186:189], v[162:165], v[82:85]
	v_mfma_f32_16x16x32_bf16 v[70:73], v[178:181], v[170:173], v[70:73]
	v_mfma_f32_16x16x32_bf16 v[66:69], v[186:189], v[170:173], v[66:69]
	v_mfma_f32_16x16x32_bf16 v[126:129], v[182:185], v[146:149], v[126:129]
	v_mfma_f32_16x16x32_bf16 v[114:117], v[216:219], v[146:149], v[114:117]
	v_mfma_f32_16x16x32_bf16 v[102:105], v[182:185], v[158:161], v[102:105]
	v_mfma_f32_16x16x32_bf16 v[98:101], v[216:219], v[158:161], v[98:101]
	v_mfma_f32_16x16x32_bf16 v[86:89], v[182:185], v[166:169], v[86:89]
	v_mfma_f32_16x16x32_bf16 v[82:85], v[216:219], v[166:169], v[82:85]
	v_mfma_f32_16x16x32_bf16 v[70:73], v[182:185], v[174:177], v[70:73]
	v_mfma_f32_16x16x32_bf16 v[66:69], v[216:219], v[174:177], v[66:69]
	s_setprio 0
	s_mov_b32 m0, s28
	s_barrier
	ds_read_b128 v[138:141], v220 offset:49152
	ds_read_b128 v[146:149], v220 offset:50176
	ds_read_b128 v[154:157], v220 offset:51200
	ds_read_b128 v[158:161], v220 offset:52224
	ds_read_b128 v[162:165], v220 offset:53248
	ds_read_b128 v[166:169], v220 offset:54272
	ds_read_b128 v[170:173], v220 offset:55296
	ds_read_b128 v[174:177], v220 offset:56320
	global_load_lds_dwordx4 v210, s[98:99]
	s_mov_b32 m0, s29
	s_nop 0
	global_load_lds_dwordx4 v206, s[98:99]
	s_barrier
	s_waitcnt lgkmcnt(0)
	s_setprio 1
	s_waitcnt lgkmcnt(0)
	v_mfma_f32_16x16x32_bf16 v[62:65], v[118:121], v[138:141], v[62:65]
	v_mfma_f32_16x16x32_bf16 v[58:61], v[130:133], v[138:141], v[58:61]
	v_mfma_f32_16x16x32_bf16 v[46:49], v[118:121], v[154:157], v[46:49]
	v_mfma_f32_16x16x32_bf16 v[42:45], v[130:133], v[154:157], v[42:45]
	v_mfma_f32_16x16x32_bf16 v[30:33], v[118:121], v[162:165], v[30:33]
	v_mfma_f32_16x16x32_bf16 v[26:29], v[130:133], v[162:165], v[26:29]
	v_mfma_f32_16x16x32_bf16 v[14:17], v[118:121], v[170:173], v[14:17]
	v_mfma_f32_16x16x32_bf16 v[10:13], v[130:133], v[170:173], v[10:13]
	v_mfma_f32_16x16x32_bf16 v[62:65], v[122:125], v[146:149], v[62:65]
	v_mfma_f32_16x16x32_bf16 v[58:61], v[134:137], v[146:149], v[58:61]
	v_mfma_f32_16x16x32_bf16 v[46:49], v[122:125], v[158:161], v[46:49]
	v_mfma_f32_16x16x32_bf16 v[42:45], v[134:137], v[158:161], v[42:45]
	v_mfma_f32_16x16x32_bf16 v[30:33], v[122:125], v[166:169], v[30:33]
	v_mfma_f32_16x16x32_bf16 v[26:29], v[134:137], v[166:169], v[26:29]
	v_mfma_f32_16x16x32_bf16 v[14:17], v[122:125], v[174:177], v[14:17]
	v_mfma_f32_16x16x32_bf16 v[10:13], v[134:137], v[174:177], v[10:13]
	s_setprio 0
	s_barrier
	s_add_u32 s16, s16, 0x40080
	s_addc_u32 s17, s17, 0
	s_add_i32 s18, s18, s22
	s_mov_b32 m0, s18
	s_nop 0
	global_load_lds_dwordx4 v208, s[16:17]
	s_add_i32 m0, s18, 0x2000
	s_nop 0
	global_load_lds_dwordx4 v204, s[16:17]
	s_waitcnt vmcnt(6)
	s_barrier
	s_setprio 1
	v_mfma_f32_16x16x32_bf16 v[54:57], v[178:181], v[138:141], v[54:57]
	v_mfma_f32_16x16x32_bf16 v[50:53], v[186:189], v[138:141], v[50:53]
	v_mfma_f32_16x16x32_bf16 v[38:41], v[178:181], v[154:157], v[38:41]
	v_mfma_f32_16x16x32_bf16 v[34:37], v[186:189], v[154:157], v[34:37]
	v_mfma_f32_16x16x32_bf16 v[22:25], v[178:181], v[162:165], v[22:25]
	v_mfma_f32_16x16x32_bf16 v[18:21], v[186:189], v[162:165], v[18:21]
	v_mfma_f32_16x16x32_bf16 v[6:9], v[178:181], v[170:173], v[6:9]
	v_mfma_f32_16x16x32_bf16 v[2:5], v[186:189], v[170:173], v[2:5]
	v_mfma_f32_16x16x32_bf16 v[54:57], v[182:185], v[146:149], v[54:57]
	v_mfma_f32_16x16x32_bf16 v[50:53], v[216:219], v[146:149], v[50:53]
	v_mfma_f32_16x16x32_bf16 v[38:41], v[182:185], v[158:161], v[38:41]
	v_mfma_f32_16x16x32_bf16 v[34:37], v[216:219], v[158:161], v[34:37]
	v_mfma_f32_16x16x32_bf16 v[22:25], v[182:185], v[166:169], v[22:25]
	v_mfma_f32_16x16x32_bf16 v[18:21], v[216:219], v[166:169], v[18:21]
	v_mfma_f32_16x16x32_bf16 v[6:9], v[182:185], v[174:177], v[6:9]
	v_mfma_f32_16x16x32_bf16 v[2:5], v[216:219], v[174:177], v[2:5]
	s_setprio 0
	s_add_i32 s46, s46, 2
	s_add_u32 s14, s14, 0x100
	s_addc_u32 s15, s15, 0
	s_add_u32 s44, s44, 0x100
	s_addc_u32 s45, s45, 0
	s_cmp_gt_u32 s46, 13
	s_barrier

.LBB0_1102:
	s_add_u32 s34, s10, 0x100
	s_addc_u32 s35, s11, 0
	s_mov_b32 s36, -2
	s_add_u32 s10, s8, 0x100
	s_addc_u32 s11, s9, 0
	s_add_i32 s37, 0, 0x10000
	v_add_u32_e32 v249, s37, v203
	ds_read_b128 v[118:121], v249
	ds_read_b128 v[122:125], v249 offset:1024
	ds_read_b128 v[130:133], v249 offset:2048
	ds_read_b128 v[134:137], v249 offset:3072
	s_cmp_eq_u32 s36, 40
	s_cselect_b32 s15, s1, s11
	s_cselect_b32 s14, s0, s10
	s_cselect_b32 s13, s3, s35
	s_cselect_b32 s12, s2, s34
	s_add_i32 m0, s19, 0xc000
	ds_read_b128 v[138:141], v220
	ds_read_b128 v[146:149], v220 offset:1024
	ds_read_b128 v[154:157], v220 offset:2048
	ds_read_b128 v[158:161], v220 offset:3072
	ds_read_b128 v[162:165], v220 offset:4096
	ds_read_b128 v[166:169], v220 offset:5120
	ds_read_b128 v[170:173], v220 offset:6144
	ds_read_b128 v[174:177], v220 offset:7168
	global_load_lds_dwordx4 v212, s[8:9]
	s_add_i32 m0, s19, 0xe000
	s_nop 0
	global_load_lds_dwordx4 v214, s[8:9]
	s_waitcnt lgkmcnt(8)
	s_barrier
	s_waitcnt lgkmcnt(0)
	s_setprio 1
	s_waitcnt lgkmcnt(0)
	v_mfma_f32_16x16x32_bf16 v[150:153], v[118:121], v[138:141], 0
	v_mfma_f32_16x16x32_bf16 v[142:145], v[130:133], v[138:141], 0
	v_mfma_f32_16x16x32_bf16 v[110:113], v[118:121], v[154:157], 0
	v_mfma_f32_16x16x32_bf16 v[106:109], v[130:133], v[154:157], 0
	v_mfma_f32_16x16x32_bf16 v[94:97], v[118:121], v[162:165], 0
	v_mfma_f32_16x16x32_bf16 v[90:93], v[130:133], v[162:165], 0
	v_mfma_f32_16x16x32_bf16 v[78:81], v[118:121], v[170:173], 0
	v_mfma_f32_16x16x32_bf16 v[74:77], v[130:133], v[170:173], 0
	v_mfma_f32_16x16x32_bf16 v[150:153], v[122:125], v[146:149], v[150:153]
	v_mfma_f32_16x16x32_bf16 v[142:145], v[134:137], v[146:149], v[142:145]
	v_mfma_f32_16x16x32_bf16 v[110:113], v[122:125], v[158:161], v[110:113]
	v_mfma_f32_16x16x32_bf16 v[106:109], v[134:137], v[158:161], v[106:109]
	v_mfma_f32_16x16x32_bf16 v[94:97], v[122:125], v[166:169], v[94:97]
	v_mfma_f32_16x16x32_bf16 v[90:93], v[134:137], v[166:169], v[90:93]
	v_mfma_f32_16x16x32_bf16 v[78:81], v[122:125], v[174:177], v[78:81]
	v_mfma_f32_16x16x32_bf16 v[74:77], v[134:137], v[174:177], v[74:77]
	s_setprio 0
	s_barrier
	s_add_i32 s44, 0, 0x14000
	s_add_i32 s8, s37, s18
	ds_read_b128 v[178:181], v249 offset:16384
	ds_read_b128 v[182:185], v249 offset:17408
	ds_read_b128 v[186:189], v249 offset:18432
	ds_read_b128 v[216:219], v249 offset:19456
	s_mov_b32 m0, s8
	s_nop 0
	global_load_lds_dwordx4 v208, s[12:13]
	s_add_i32 m0, s8, 0x2000
	s_nop 0
	global_load_lds_dwordx4 v204, s[12:13]
	s_barrier
	s_waitcnt lgkmcnt(0)
	s_setprio 1
	s_waitcnt lgkmcnt(0)
	v_mfma_f32_16x16x32_bf16 v[126:129], v[178:181], v[138:141], 0
	v_mfma_f32_16x16x32_bf16 v[114:117], v[186:189], v[138:141], 0
	v_mfma_f32_16x16x32_bf16 v[102:105], v[178:181], v[154:157], 0
	v_mfma_f32_16x16x32_bf16 v[98:101], v[186:189], v[154:157], 0
	v_mfma_f32_16x16x32_bf16 v[86:89], v[178:181], v[162:165], 0
	v_mfma_f32_16x16x32_bf16 v[82:85], v[186:189], v[162:165], 0
	v_mfma_f32_16x16x32_bf16 v[70:73], v[178:181], v[170:173], 0
	v_mfma_f32_16x16x32_bf16 v[66:69], v[186:189], v[170:173], 0
	v_mfma_f32_16x16x32_bf16 v[126:129], v[182:185], v[146:149], v[126:129]
	v_mfma_f32_16x16x32_bf16 v[114:117], v[216:219], v[146:149], v[114:117]
	v_mfma_f32_16x16x32_bf16 v[102:105], v[182:185], v[158:161], v[102:105]
	v_mfma_f32_16x16x32_bf16 v[98:101], v[216:219], v[158:161], v[98:101]
	v_mfma_f32_16x16x32_bf16 v[86:89], v[182:185], v[166:169], v[86:89]
	v_mfma_f32_16x16x32_bf16 v[82:85], v[216:219], v[166:169], v[82:85]
	v_mfma_f32_16x16x32_bf16 v[70:73], v[182:185], v[174:177], v[70:73]
	v_mfma_f32_16x16x32_bf16 v[66:69], v[216:219], v[174:177], v[66:69]
	s_setprio 0
	s_mov_b32 m0, s19
	s_add_u32 s98, s14, 0x80
	s_addc_u32 s99, s15, 0
	s_barrier
	ds_read_b128 v[138:141], v220 offset:16384
	ds_read_b128 v[146:149], v220 offset:17408
	ds_read_b128 v[154:157], v220 offset:18432
	ds_read_b128 v[158:161], v220 offset:19456
	ds_read_b128 v[162:165], v220 offset:20480
	ds_read_b128 v[166:169], v220 offset:21504
	ds_read_b128 v[170:173], v220 offset:22528
	ds_read_b128 v[174:177], v220 offset:23552
	global_load_lds_dwordx4 v210, s[14:15]
	s_mov_b32 m0, s20
	s_nop 0
	global_load_lds_dwordx4 v206, s[14:15]
	s_barrier
	s_waitcnt lgkmcnt(0)
	s_setprio 1
	s_waitcnt lgkmcnt(0)
	v_mfma_f32_16x16x32_bf16 v[62:65], v[118:121], v[138:141], 0
	v_mfma_f32_16x16x32_bf16 v[58:61], v[130:133], v[138:141], 0
	v_mfma_f32_16x16x32_bf16 v[46:49], v[118:121], v[154:157], 0
	v_mfma_f32_16x16x32_bf16 v[42:45], v[130:133], v[154:157], 0
	v_mfma_f32_16x16x32_bf16 v[30:33], v[118:121], v[162:165], 0
	v_mfma_f32_16x16x32_bf16 v[26:29], v[130:133], v[162:165], 0
	v_mfma_f32_16x16x32_bf16 v[14:17], v[118:121], v[170:173], 0
	v_mfma_f32_16x16x32_bf16 v[10:13], v[130:133], v[170:173], 0
	v_mfma_f32_16x16x32_bf16 v[62:65], v[122:125], v[146:149], v[62:65]
	v_mfma_f32_16x16x32_bf16 v[58:61], v[134:137], v[146:149], v[58:61]
	v_mfma_f32_16x16x32_bf16 v[46:49], v[122:125], v[158:161], v[46:49]
	v_mfma_f32_16x16x32_bf16 v[42:45], v[134:137], v[158:161], v[42:45]
	v_mfma_f32_16x16x32_bf16 v[30:33], v[122:125], v[166:169], v[30:33]
	v_mfma_f32_16x16x32_bf16 v[26:29], v[134:137], v[166:169], v[26:29]
	v_mfma_f32_16x16x32_bf16 v[14:17], v[122:125], v[174:177], v[14:17]
	v_mfma_f32_16x16x32_bf16 v[10:13], v[134:137], v[174:177], v[10:13]
	s_setprio 0
	s_barrier
	s_add_u32 s8, s12, 0xb0000
	s_addc_u32 s9, s13, 0
	s_add_i32 s37, s44, s18
	s_mov_b32 m0, s37
	s_nop 0
	global_load_lds_dwordx4 v208, s[8:9]
	s_add_i32 m0, s37, 0x2000
	s_nop 0
	global_load_lds_dwordx4 v204, s[8:9]
	s_waitcnt vmcnt(6)
	s_barrier
	s_setprio 1
	v_mfma_f32_16x16x32_bf16 v[54:57], v[178:181], v[138:141], 0
	v_mfma_f32_16x16x32_bf16 v[50:53], v[186:189], v[138:141], 0
	v_mfma_f32_16x16x32_bf16 v[38:41], v[178:181], v[154:157], 0
	v_mfma_f32_16x16x32_bf16 v[34:37], v[186:189], v[154:157], 0
	v_mfma_f32_16x16x32_bf16 v[22:25], v[178:181], v[162:165], 0
	v_mfma_f32_16x16x32_bf16 v[18:21], v[186:189], v[162:165], 0
	v_mfma_f32_16x16x32_bf16 v[6:9], v[178:181], v[170:173], 0
	v_mfma_f32_16x16x32_bf16 v[2:5], v[186:189], v[170:173], 0
	v_mfma_f32_16x16x32_bf16 v[54:57], v[182:185], v[146:149], v[54:57]
	v_mfma_f32_16x16x32_bf16 v[50:53], v[216:219], v[146:149], v[50:53]
	v_mfma_f32_16x16x32_bf16 v[38:41], v[182:185], v[158:161], v[38:41]
	v_mfma_f32_16x16x32_bf16 v[34:37], v[216:219], v[158:161], v[34:37]
	v_mfma_f32_16x16x32_bf16 v[22:25], v[182:185], v[166:169], v[22:25]
	v_mfma_f32_16x16x32_bf16 v[18:21], v[216:219], v[166:169], v[18:21]
	v_mfma_f32_16x16x32_bf16 v[6:9], v[182:185], v[174:177], v[6:9]
	v_mfma_f32_16x16x32_bf16 v[2:5], v[216:219], v[174:177], v[2:5]
	s_setprio 0
	s_add_i32 s37, 0, 0x18000
	s_barrier
	ds_read_b128 v[118:121], v249 offset:32768
	ds_read_b128 v[122:125], v249 offset:33792
	ds_read_b128 v[130:133], v249 offset:34816
	ds_read_b128 v[134:137], v249 offset:35840
	s_add_u32 s8, s14, 0xb0000
	s_addc_u32 s9, s15, 0
	s_mov_b32 m0, s21
	ds_read_b128 v[138:141], v220 offset:32768
	ds_read_b128 v[146:149], v220 offset:33792
	ds_read_b128 v[154:157], v220 offset:34816
	ds_read_b128 v[158:161], v220 offset:35840
	ds_read_b128 v[162:165], v220 offset:36864
	ds_read_b128 v[166:169], v220 offset:37888
	ds_read_b128 v[170:173], v220 offset:38912
	ds_read_b128 v[174:177], v220 offset:39936
	global_load_lds_dwordx4 v210, s[8:9]
	s_mov_b32 m0, s22
	s_nop 0
	global_load_lds_dwordx4 v206, s[8:9]
	s_waitcnt lgkmcnt(8)
	s_barrier
	s_waitcnt lgkmcnt(0)
	s_setprio 1
	s_waitcnt lgkmcnt(0)
	v_mfma_f32_16x16x32_bf16 v[150:153], v[118:121], v[138:141], v[150:153]
	v_mfma_f32_16x16x32_bf16 v[142:145], v[130:133], v[138:141], v[142:145]
	v_mfma_f32_16x16x32_bf16 v[110:113], v[118:121], v[154:157], v[110:113]
	v_mfma_f32_16x16x32_bf16 v[106:109], v[130:133], v[154:157], v[106:109]
	v_mfma_f32_16x16x32_bf16 v[94:97], v[118:121], v[162:165], v[94:97]
	v_mfma_f32_16x16x32_bf16 v[90:93], v[130:133], v[162:165], v[90:93]
	v_mfma_f32_16x16x32_bf16 v[78:81], v[118:121], v[170:173], v[78:81]
	v_mfma_f32_16x16x32_bf16 v[74:77], v[130:133], v[170:173], v[74:77]
	v_mfma_f32_16x16x32_bf16 v[150:153], v[122:125], v[146:149], v[150:153]
	v_mfma_f32_16x16x32_bf16 v[142:145], v[134:137], v[146:149], v[142:145]
	v_mfma_f32_16x16x32_bf16 v[110:113], v[122:125], v[158:161], v[110:113]
	v_mfma_f32_16x16x32_bf16 v[106:109], v[134:137], v[158:161], v[106:109]
	v_mfma_f32_16x16x32_bf16 v[94:97], v[122:125], v[166:169], v[94:97]
	v_mfma_f32_16x16x32_bf16 v[90:93], v[134:137], v[166:169], v[90:93]
	v_mfma_f32_16x16x32_bf16 v[78:81], v[122:125], v[174:177], v[78:81]
	v_mfma_f32_16x16x32_bf16 v[74:77], v[134:137], v[174:177], v[74:77]
	s_setprio 0
	s_barrier
	s_add_i32 s14, 0, 0x1c000
	s_add_i32 s8, s37, s18
	s_add_u32 vcc_lo, s12, 0x80
	s_addc_u32 vcc_hi, s13, 0
	s_mov_b32 m0, s8
	ds_read_b128 v[178:181], v249 offset:49152
	ds_read_b128 v[182:185], v249 offset:50176
	ds_read_b128 v[186:189], v249 offset:51200
	ds_read_b128 v[216:219], v249 offset:52224
	global_load_lds_dwordx4 v208, vcc
	s_add_i32 m0, s8, 0x2000
	s_nop 0
	global_load_lds_dwordx4 v204, vcc
	s_barrier
	s_waitcnt lgkmcnt(0)
	s_setprio 1
	s_waitcnt lgkmcnt(0)
	v_mfma_f32_16x16x32_bf16 v[126:129], v[178:181], v[138:141], v[126:129]
	v_mfma_f32_16x16x32_bf16 v[114:117], v[186:189], v[138:141], v[114:117]
	v_mfma_f32_16x16x32_bf16 v[102:105], v[178:181], v[154:157], v[102:105]
	v_mfma_f32_16x16x32_bf16 v[98:101], v[186:189], v[154:157], v[98:101]
	v_mfma_f32_16x16x32_bf16 v[86:89], v[178:181], v[162:165], v[86:89]
	v_mfma_f32_16x16x32_bf16 v[82:85], v[186:189], v[162:165], v[82:85]
	v_mfma_f32_16x16x32_bf16 v[70:73], v[178:181], v[170:173], v[70:73]
	v_mfma_f32_16x16x32_bf16 v[66:69], v[186:189], v[170:173], v[66:69]
	v_mfma_f32_16x16x32_bf16 v[126:129], v[182:185], v[146:149], v[126:129]
	v_mfma_f32_16x16x32_bf16 v[114:117], v[216:219], v[146:149], v[114:117]
	v_mfma_f32_16x16x32_bf16 v[102:105], v[182:185], v[158:161], v[102:105]
	v_mfma_f32_16x16x32_bf16 v[98:101], v[216:219], v[158:161], v[98:101]
	v_mfma_f32_16x16x32_bf16 v[86:89], v[182:185], v[166:169], v[86:89]
	v_mfma_f32_16x16x32_bf16 v[82:85], v[216:219], v[166:169], v[82:85]
	v_mfma_f32_16x16x32_bf16 v[70:73], v[182:185], v[174:177], v[70:73]
	v_mfma_f32_16x16x32_bf16 v[66:69], v[216:219], v[174:177], v[66:69]
	s_setprio 0
	s_mov_b32 m0, s24
	s_barrier
	ds_read_b128 v[138:141], v220 offset:49152
	ds_read_b128 v[146:149], v220 offset:50176
	ds_read_b128 v[154:157], v220 offset:51200
	ds_read_b128 v[158:161], v220 offset:52224
	ds_read_b128 v[162:165], v220 offset:53248
	ds_read_b128 v[166:169], v220 offset:54272
	ds_read_b128 v[170:173], v220 offset:55296
	ds_read_b128 v[174:177], v220 offset:56320
	global_load_lds_dwordx4 v210, s[98:99]
	s_mov_b32 m0, s25
	s_nop 0
	global_load_lds_dwordx4 v206, s[98:99]
	s_barrier
	s_waitcnt lgkmcnt(0)
	s_setprio 1
	s_waitcnt lgkmcnt(0)
	v_mfma_f32_16x16x32_bf16 v[62:65], v[118:121], v[138:141], v[62:65]
	v_mfma_f32_16x16x32_bf16 v[58:61], v[130:133], v[138:141], v[58:61]
	v_mfma_f32_16x16x32_bf16 v[46:49], v[118:121], v[154:157], v[46:49]
	v_mfma_f32_16x16x32_bf16 v[42:45], v[130:133], v[154:157], v[42:45]
	v_mfma_f32_16x16x32_bf16 v[30:33], v[118:121], v[162:165], v[30:33]
	v_mfma_f32_16x16x32_bf16 v[26:29], v[130:133], v[162:165], v[26:29]
	v_mfma_f32_16x16x32_bf16 v[14:17], v[118:121], v[170:173], v[14:17]
	v_mfma_f32_16x16x32_bf16 v[10:13], v[130:133], v[170:173], v[10:13]
	v_mfma_f32_16x16x32_bf16 v[62:65], v[122:125], v[146:149], v[62:65]
	v_mfma_f32_16x16x32_bf16 v[58:61], v[134:137], v[146:149], v[58:61]
	v_mfma_f32_16x16x32_bf16 v[46:49], v[122:125], v[158:161], v[46:49]
	v_mfma_f32_16x16x32_bf16 v[42:45], v[134:137], v[158:161], v[42:45]
	v_mfma_f32_16x16x32_bf16 v[30:33], v[122:125], v[166:169], v[30:33]
	v_mfma_f32_16x16x32_bf16 v[26:29], v[134:137], v[166:169], v[26:29]
	v_mfma_f32_16x16x32_bf16 v[14:17], v[122:125], v[174:177], v[14:17]
	v_mfma_f32_16x16x32_bf16 v[10:13], v[134:137], v[174:177], v[10:13]
	s_setprio 0
	s_barrier
	s_add_u32 s8, s12, 0xb0080
	s_addc_u32 s9, s13, 0
	s_add_i32 s12, s14, s18
	s_mov_b32 m0, s12
	s_nop 0
	global_load_lds_dwordx4 v208, s[8:9]
	s_add_i32 m0, s12, 0x2000
	s_nop 0
	global_load_lds_dwordx4 v204, s[8:9]
	s_waitcnt vmcnt(6)
	s_barrier
	s_setprio 1
	v_mfma_f32_16x16x32_bf16 v[54:57], v[178:181], v[138:141], v[54:57]
	v_mfma_f32_16x16x32_bf16 v[50:53], v[186:189], v[138:141], v[50:53]
	v_mfma_f32_16x16x32_bf16 v[38:41], v[178:181], v[154:157], v[38:41]
	v_mfma_f32_16x16x32_bf16 v[34:37], v[186:189], v[154:157], v[34:37]
	v_mfma_f32_16x16x32_bf16 v[22:25], v[178:181], v[162:165], v[22:25]
	v_mfma_f32_16x16x32_bf16 v[18:21], v[186:189], v[162:165], v[18:21]
	v_mfma_f32_16x16x32_bf16 v[6:9], v[178:181], v[170:173], v[6:9]
	v_mfma_f32_16x16x32_bf16 v[2:5], v[186:189], v[170:173], v[2:5]
	v_mfma_f32_16x16x32_bf16 v[54:57], v[182:185], v[146:149], v[54:57]
	v_mfma_f32_16x16x32_bf16 v[50:53], v[216:219], v[146:149], v[50:53]
	v_mfma_f32_16x16x32_bf16 v[38:41], v[182:185], v[158:161], v[38:41]
	v_mfma_f32_16x16x32_bf16 v[34:37], v[216:219], v[158:161], v[34:37]
	v_mfma_f32_16x16x32_bf16 v[22:25], v[182:185], v[166:169], v[22:25]
	v_mfma_f32_16x16x32_bf16 v[18:21], v[216:219], v[166:169], v[18:21]
	v_mfma_f32_16x16x32_bf16 v[6:9], v[182:185], v[174:177], v[6:9]
	v_mfma_f32_16x16x32_bf16 v[2:5], v[216:219], v[174:177], v[2:5]
	s_setprio 0
	s_add_i32 s36, s36, 2
	s_add_u32 s34, s34, 0x100
	s_addc_u32 s35, s35, 0
	s_cmp_gt_u32 s36, 41
	s_mov_b64 s[8:9], s[10:11]
	s_barrier

.LBB0_1147:
	s_lshl_b32 s0, s0, 5
	s_and_b32 s10, s0, 0x60
	s_lshl_b32 s3, s2, 13
	s_lshl_b32 s7, s10, 7
	s_add_u32 s0, s72, 0x5195000
	s_addc_u32 s1, s73, 0
	s_add_i32 m0, s9, 0x18000
	v_lshl_add_u64 v[8:9], v[8:9], 0, s[78:79]
	s_waitcnt vmcnt(2)
	s_barrier
	global_load_lds_dwordx4 v[8:9], off
	v_lshl_add_u64 v[6:7], v[6:7], 0, s[78:79]
	s_add_i32 m0, s9, 0x1a000
	s_add_i32 s29, s9, 0x8000
	s_add_i32 s30, s9, 0xa000
	global_load_lds_dwordx4 v[6:7], off
	v_lshl_add_u64 v[4:5], v[4:5], 0, s[78:79]
	s_mov_b32 m0, s29
	s_add_u32 s4, s16, 0x40080
	global_load_lds_dwordx4 v[4:5], off
	v_lshl_add_u64 v[2:3], v[2:3], 0, s[78:79]
	s_mov_b32 m0, s30
	s_addc_u32 s5, s17, 0
	global_load_lds_dwordx4 v[2:3], off
	s_add_i32 m0, s9, 0x1c000
	v_lshl_add_u64 v[2:3], s[4:5], 0, v[132:133]
	global_load_lds_dwordx4 v[2:3], off
	v_lshl_add_u64 v[2:3], s[4:5], 0, v[136:137]
	s_add_i32 m0, s9, 0x1e000
	v_mov_b32_e32 v139, v191
	global_load_lds_dwordx4 v[2:3], off
	v_lshrrev_b32_e32 v2, 1, v10
	v_and_b32_e32 v2, 24, v2
	v_and_b32_e32 v3, 15, v10
	v_lshlrev_b32_e32 v4, 1, v2
	v_lshl_or_b32 v145, s2, 6, v3
	v_lshl_or_b32 v3, v3, 6, v4
	v_lshlrev_b32_e32 v4, 2, v10
	v_and_b32_e32 v4, 32, v4
	v_bitop3_b32 v5, v3, s3, v4 bitop3:0xde
	v_bitop3_b32 v154, v3, s7, v4 bitop3:0xde
	v_lshlrev_b32_e32 v3, 14, v11
	v_and_b32_e32 v3, 0xffff8000, v3
	v_lshl_add_u32 v3, v12, 11, v3
	v_and_b32_e32 v4, 1, v11
	v_lshl_or_b32 v3, v4, 6, v3
	v_lshl_add_u32 v138, v13, 1, v3
	v_lshlrev_b32_e32 v3, 14, v14
	v_and_b32_e32 v3, 0xffff8000, v3
	s_waitcnt vmcnt(6)
	v_lshl_add_u32 v3, v15, 11, v3
	v_and_b32_e32 v4, 1, v14
	v_lshl_or_b32 v3, v4, 6, v3
	v_or_b32_e32 v155, s10, v2
	v_or_b32_e32 v156, 16, v145
	v_or_b32_e32 v157, 32, v145
	v_or_b32_e32 v158, 48, v145
	v_add_u32_e32 v159, 0x80, v145
	v_add_u32_e32 v160, 0x90, v145
	v_add_u32_e32 v161, 0xa0, v145
	v_add_u32_e32 v162, 0xb0, v145
	v_lshl_add_u32 v140, v16, 1, v3
	v_mov_b32_e32 v141, v191
	s_mov_b32 s7, 0
	v_add_u32_e32 v163, 0, v5
	s_lshl_b32 s96, s10, 1
	v_lshlrev_b32_e32 v142, 1, v2
	s_barrier
	s_branch .LBB0_1149

.LBB0_1155:
	v_mov_b64_e32 v[2:3], 0x294
	s_ashr_i32 s5, s4, 31
	v_cmp_lt_i64_e32 vcc, s[10:11], v[2:3]
	s_lshl_b64 s[10:11], s[4:5], 19
	s_add_u32 s10, s46, s10
	s_addc_u32 s11, s47, s11
	s_and_b64 s[12:13], vcc, exec
	s_cselect_b32 s5, s11, s15
	s_cselect_b32 s34, s10, s14
	s_ashr_i32 s3, s2, 31
	s_lshl_b64 s[12:13], s[2:3], 19
	s_add_u32 s12, s23, s12
	s_addc_u32 s13, s24, s13
	s_and_b64 s[18:19], vcc, exec
	s_cselect_b32 s3, s13, s17
	s_cselect_b32 s35, s12, s16
	s_add_u32 s14, s14, 0x40080
	s_addc_u32 s15, s15, 0
	s_add_u32 s36, s16, 0x100
	s_addc_u32 s37, s17, 0
	s_mov_b32 s40, -2
	s_add_u32 s16, s14, 0xfffc0080
	s_addc_u32 s17, s15, -1
	s_add_i32 s41, 0, 0x10000
	v_add_u32_e32 v249, s41, v154
	ds_read_b128 v[146:149], v249
	ds_read_b128 v[150:153], v249 offset:1024
	ds_read_b128 v[164:167], v249 offset:2048
	ds_read_b128 v[168:171], v249 offset:3072
	s_cmp_eq_u32 s40, 12
	s_cselect_b32 s19, s5, s17
	s_cselect_b32 s18, s34, s16
	s_cselect_b32 s17, s3, s37
	s_cselect_b32 s16, s35, s36
	s_add_i32 s44, 0, 0x14000
	ds_read_b128 v[220:223], v249 offset:16384
	ds_read_b128 v[224:227], v249 offset:17408
	ds_read_b128 v[228:231], v249 offset:18432
	ds_read_b128 v[232:235], v249 offset:19456
	s_add_i32 m0, s9, 0xc000
	ds_read_b128 v[172:175], v163
	ds_read_b128 v[176:179], v163 offset:1024
	ds_read_b128 v[180:183], v163 offset:2048
	ds_read_b128 v[184:187], v163 offset:3072
	ds_read_b128 v[204:207], v163 offset:4096
	ds_read_b128 v[208:211], v163 offset:5120
	ds_read_b128 v[212:215], v163 offset:6144
	ds_read_b128 v[216:219], v163 offset:7168
	global_load_lds_dwordx4 v138, s[14:15]
	s_add_i32 m0, s9, 0xe000
	s_nop 0
	global_load_lds_dwordx4 v140, s[14:15]
	s_waitcnt vmcnt(8) lgkmcnt(0)
	s_barrier
	s_setprio 1
	v_mfma_f32_16x16x32_bf16 v[126:129], v[146:149], v[172:175], 0
	v_mfma_f32_16x16x32_bf16 v[122:125], v[164:167], v[172:175], 0
	v_mfma_f32_16x16x32_bf16 v[114:117], v[146:149], v[180:183], 0
	v_mfma_f32_16x16x32_bf16 v[106:109], v[164:167], v[180:183], 0
	v_mfma_f32_16x16x32_bf16 v[98:101], v[146:149], v[204:207], 0
	v_mfma_f32_16x16x32_bf16 v[90:93], v[164:167], v[204:207], 0
	v_mfma_f32_16x16x32_bf16 v[82:85], v[146:149], v[212:215], 0
	v_mfma_f32_16x16x32_bf16 v[74:77], v[164:167], v[212:215], 0
	v_mfma_f32_16x16x32_bf16 v[126:129], v[150:153], v[176:179], v[126:129]
	v_mfma_f32_16x16x32_bf16 v[122:125], v[168:171], v[176:179], v[122:125]
	v_mfma_f32_16x16x32_bf16 v[114:117], v[150:153], v[184:187], v[114:117]
	v_mfma_f32_16x16x32_bf16 v[106:109], v[168:171], v[184:187], v[106:109]
	v_mfma_f32_16x16x32_bf16 v[98:101], v[150:153], v[208:211], v[98:101]
	v_mfma_f32_16x16x32_bf16 v[90:93], v[168:171], v[208:211], v[90:93]
	v_mfma_f32_16x16x32_bf16 v[82:85], v[150:153], v[216:219], v[82:85]
	v_mfma_f32_16x16x32_bf16 v[74:77], v[168:171], v[216:219], v[74:77]
	v_mfma_f32_16x16x32_bf16 v[118:121], v[220:223], v[172:175], 0
	v_mfma_f32_16x16x32_bf16 v[110:113], v[228:231], v[172:175], 0
	v_mfma_f32_16x16x32_bf16 v[102:105], v[220:223], v[180:183], 0
	v_mfma_f32_16x16x32_bf16 v[94:97], v[228:231], v[180:183], 0
	v_mfma_f32_16x16x32_bf16 v[86:89], v[220:223], v[204:207], 0
	v_mfma_f32_16x16x32_bf16 v[78:81], v[228:231], v[204:207], 0
	v_mfma_f32_16x16x32_bf16 v[70:73], v[220:223], v[212:215], 0
	v_mfma_f32_16x16x32_bf16 v[66:69], v[228:231], v[212:215], 0
	v_mfma_f32_16x16x32_bf16 v[118:121], v[224:227], v[176:179], v[118:121]
	v_mfma_f32_16x16x32_bf16 v[110:113], v[232:235], v[176:179], v[110:113]
	v_mfma_f32_16x16x32_bf16 v[102:105], v[224:227], v[184:187], v[102:105]
	v_mfma_f32_16x16x32_bf16 v[94:97], v[232:235], v[184:187], v[94:97]
	v_mfma_f32_16x16x32_bf16 v[86:89], v[224:227], v[208:211], v[86:89]
	v_mfma_f32_16x16x32_bf16 v[78:81], v[232:235], v[208:211], v[78:81]
	v_mfma_f32_16x16x32_bf16 v[70:73], v[224:227], v[216:219], v[70:73]
	v_mfma_f32_16x16x32_bf16 v[66:69], v[232:235], v[216:219], v[66:69]
	s_setprio 0
	s_barrier
	ds_read_b128 v[172:175], v163 offset:16384
	ds_read_b128 v[176:179], v163 offset:17408
	ds_read_b128 v[180:183], v163 offset:18432
	ds_read_b128 v[184:187], v163 offset:19456
	ds_read_b128 v[204:207], v163 offset:20480
	ds_read_b128 v[208:211], v163 offset:21504
	ds_read_b128 v[212:215], v163 offset:22528
	ds_read_b128 v[216:219], v163 offset:23552
	s_add_i32 s41, s41, s25
	s_mov_b32 m0, s41
	s_nop 0
	global_load_lds_dwordx4 v132, s[16:17]
	s_add_i32 m0, s41, 0x2000
	s_nop 0
	global_load_lds_dwordx4 v136, s[16:17]
	s_mov_b32 m0, s9
	s_add_u32 s98, s18, 0x80
	s_addc_u32 s99, s19, 0
	global_load_lds_dwordx4 v130, s[18:19]
	s_mov_b32 m0, s26
	s_nop 0
	global_load_lds_dwordx4 v134, s[18:19]
	s_add_u32 s42, s16, 0x40000
	s_addc_u32 s43, s17, 0
	s_add_i32 s41, s44, s25
	s_mov_b32 m0, s41
	s_nop 0
	global_load_lds_dwordx4 v132, s[42:43]
	s_add_i32 m0, s41, 0x2000
	s_nop 0
	global_load_lds_dwordx4 v136, s[42:43]
	s_waitcnt vmcnt(8) lgkmcnt(0)
	s_barrier
	s_setprio 1
	v_mfma_f32_16x16x32_bf16 v[62:65], v[146:149], v[172:175], 0
	v_mfma_f32_16x16x32_bf16 v[58:61], v[164:167], v[172:175], 0
	v_mfma_f32_16x16x32_bf16 v[50:53], v[146:149], v[180:183], 0
	v_mfma_f32_16x16x32_bf16 v[42:45], v[164:167], v[180:183], 0
	v_mfma_f32_16x16x32_bf16 v[34:37], v[146:149], v[204:207], 0
	v_mfma_f32_16x16x32_bf16 v[26:29], v[164:167], v[204:207], 0
	v_mfma_f32_16x16x32_bf16 v[18:21], v[146:149], v[212:215], 0
	v_mfma_f32_16x16x32_bf16 v[10:13], v[164:167], v[212:215], 0
	v_mfma_f32_16x16x32_bf16 v[62:65], v[150:153], v[176:179], v[62:65]
	v_mfma_f32_16x16x32_bf16 v[58:61], v[168:171], v[176:179], v[58:61]
	v_mfma_f32_16x16x32_bf16 v[50:53], v[150:153], v[184:187], v[50:53]
	v_mfma_f32_16x16x32_bf16 v[42:45], v[168:171], v[184:187], v[42:45]
	v_mfma_f32_16x16x32_bf16 v[34:37], v[150:153], v[208:211], v[34:37]
	v_mfma_f32_16x16x32_bf16 v[26:29], v[168:171], v[208:211], v[26:29]
	v_mfma_f32_16x16x32_bf16 v[18:21], v[150:153], v[216:219], v[18:21]
	v_mfma_f32_16x16x32_bf16 v[10:13], v[168:171], v[216:219], v[10:13]
	v_mfma_f32_16x16x32_bf16 v[54:57], v[220:223], v[172:175], 0
	v_mfma_f32_16x16x32_bf16 v[46:49], v[228:231], v[172:175], 0
	v_mfma_f32_16x16x32_bf16 v[38:41], v[220:223], v[180:183], 0
	v_mfma_f32_16x16x32_bf16 v[30:33], v[228:231], v[180:183], 0
	v_mfma_f32_16x16x32_bf16 v[22:25], v[220:223], v[204:207], 0
	v_mfma_f32_16x16x32_bf16 v[14:17], v[228:231], v[204:207], 0
	v_mfma_f32_16x16x32_bf16 v[6:9], v[220:223], v[212:215], 0
	v_mfma_f32_16x16x32_bf16 v[2:5], v[228:231], v[212:215], 0
	v_mfma_f32_16x16x32_bf16 v[54:57], v[224:227], v[176:179], v[54:57]
	v_mfma_f32_16x16x32_bf16 v[46:49], v[232:235], v[176:179], v[46:49]
	v_mfma_f32_16x16x32_bf16 v[38:41], v[224:227], v[184:187], v[38:41]
	v_mfma_f32_16x16x32_bf16 v[30:33], v[232:235], v[184:187], v[30:33]
	v_mfma_f32_16x16x32_bf16 v[22:25], v[224:227], v[208:211], v[22:25]
	v_mfma_f32_16x16x32_bf16 v[14:17], v[232:235], v[208:211], v[14:17]
	v_mfma_f32_16x16x32_bf16 v[6:9], v[224:227], v[216:219], v[6:9]
	v_mfma_f32_16x16x32_bf16 v[2:5], v[232:235], v[216:219], v[2:5]
	s_setprio 0
	s_barrier
	s_add_i32 s41, 0, 0x18000
	ds_read_b128 v[146:149], v249 offset:32768
	ds_read_b128 v[150:153], v249 offset:33792
	ds_read_b128 v[164:167], v249 offset:34816
	ds_read_b128 v[168:171], v249 offset:35840
	s_add_u32 s18, s18, 0x40000
	s_addc_u32 s19, s19, 0
	s_mov_b32 m0, s27
	ds_read_b128 v[172:175], v163 offset:32768
	ds_read_b128 v[176:179], v163 offset:33792
	ds_read_b128 v[180:183], v163 offset:34816
	ds_read_b128 v[184:187], v163 offset:35840
	ds_read_b128 v[204:207], v163 offset:36864
	ds_read_b128 v[208:211], v163 offset:37888
	ds_read_b128 v[212:215], v163 offset:38912
	ds_read_b128 v[216:219], v163 offset:39936
	global_load_lds_dwordx4 v130, s[18:19]
	s_mov_b32 m0, s28
	s_nop 0
	global_load_lds_dwordx4 v134, s[18:19]
	s_add_i32 s18, 0, 0x1c000
	ds_read_b128 v[220:223], v249 offset:49152
	ds_read_b128 v[224:227], v249 offset:50176
	ds_read_b128 v[228:231], v249 offset:51200
	ds_read_b128 v[232:235], v249 offset:52224
	s_waitcnt vmcnt(8) lgkmcnt(0)
	s_barrier
	s_setprio 1
	v_mfma_f32_16x16x32_bf16 v[126:129], v[146:149], v[172:175], v[126:129]
	v_mfma_f32_16x16x32_bf16 v[122:125], v[164:167], v[172:175], v[122:125]
	v_mfma_f32_16x16x32_bf16 v[114:117], v[146:149], v[180:183], v[114:117]
	v_mfma_f32_16x16x32_bf16 v[106:109], v[164:167], v[180:183], v[106:109]
	v_mfma_f32_16x16x32_bf16 v[98:101], v[146:149], v[204:207], v[98:101]
	v_mfma_f32_16x16x32_bf16 v[90:93], v[164:167], v[204:207], v[90:93]
	v_mfma_f32_16x16x32_bf16 v[82:85], v[146:149], v[212:215], v[82:85]
	v_mfma_f32_16x16x32_bf16 v[74:77], v[164:167], v[212:215], v[74:77]
	v_mfma_f32_16x16x32_bf16 v[126:129], v[150:153], v[176:179], v[126:129]
	v_mfma_f32_16x16x32_bf16 v[122:125], v[168:171], v[176:179], v[122:125]
	v_mfma_f32_16x16x32_bf16 v[114:117], v[150:153], v[184:187], v[114:117]
	v_mfma_f32_16x16x32_bf16 v[106:109], v[168:171], v[184:187], v[106:109]
	v_mfma_f32_16x16x32_bf16 v[98:101], v[150:153], v[208:211], v[98:101]
	v_mfma_f32_16x16x32_bf16 v[90:93], v[168:171], v[208:211], v[90:93]
	v_mfma_f32_16x16x32_bf16 v[82:85], v[150:153], v[216:219], v[82:85]
	v_mfma_f32_16x16x32_bf16 v[74:77], v[168:171], v[216:219], v[74:77]
	v_mfma_f32_16x16x32_bf16 v[118:121], v[220:223], v[172:175], v[118:121]
	v_mfma_f32_16x16x32_bf16 v[110:113], v[228:231], v[172:175], v[110:113]
	v_mfma_f32_16x16x32_bf16 v[102:105], v[220:223], v[180:183], v[102:105]
	v_mfma_f32_16x16x32_bf16 v[94:97], v[228:231], v[180:183], v[94:97]
	v_mfma_f32_16x16x32_bf16 v[86:89], v[220:223], v[204:207], v[86:89]
	v_mfma_f32_16x16x32_bf16 v[78:81], v[228:231], v[204:207], v[78:81]
	v_mfma_f32_16x16x32_bf16 v[70:73], v[220:223], v[212:215], v[70:73]
	v_mfma_f32_16x16x32_bf16 v[66:69], v[228:231], v[212:215], v[66:69]
	v_mfma_f32_16x16x32_bf16 v[118:121], v[224:227], v[176:179], v[118:121]
	v_mfma_f32_16x16x32_bf16 v[110:113], v[232:235], v[176:179], v[110:113]
	v_mfma_f32_16x16x32_bf16 v[102:105], v[224:227], v[184:187], v[102:105]
	v_mfma_f32_16x16x32_bf16 v[94:97], v[232:235], v[184:187], v[94:97]
	v_mfma_f32_16x16x32_bf16 v[86:89], v[224:227], v[208:211], v[86:89]
	v_mfma_f32_16x16x32_bf16 v[78:81], v[232:235], v[208:211], v[78:81]
	v_mfma_f32_16x16x32_bf16 v[70:73], v[224:227], v[216:219], v[70:73]
	v_mfma_f32_16x16x32_bf16 v[66:69], v[232:235], v[216:219], v[66:69]
	s_setprio 0
	s_barrier
	ds_read_b128 v[172:175], v163 offset:49152
	ds_read_b128 v[176:179], v163 offset:50176
	ds_read_b128 v[180:183], v163 offset:51200
	ds_read_b128 v[184:187], v163 offset:52224
	ds_read_b128 v[204:207], v163 offset:53248
	ds_read_b128 v[208:211], v163 offset:54272
	ds_read_b128 v[212:215], v163 offset:55296
	ds_read_b128 v[216:219], v163 offset:56320
	s_add_i32 s19, s41, s25
	s_mov_b32 m0, s19
	s_add_u32 vcc_lo, s16, 0x80
	s_addc_u32 vcc_hi, s17, 0
	global_load_lds_dwordx4 v132, vcc
	s_add_i32 m0, s19, 0x2000
	s_nop 0
	global_load_lds_dwordx4 v136, vcc
	s_mov_b32 m0, s29
	s_nop 0
	global_load_lds_dwordx4 v130, s[98:99]
	s_mov_b32 m0, s30
	s_nop 0
	global_load_lds_dwordx4 v134, s[98:99]
	s_add_u32 s16, s16, 0x40080
	s_addc_u32 s17, s17, 0
	s_add_i32 s18, s18, s25
	s_mov_b32 m0, s18
	s_nop 0
	global_load_lds_dwordx4 v132, s[16:17]
	s_add_i32 m0, s18, 0x2000
	s_nop 0
	global_load_lds_dwordx4 v136, s[16:17]
	s_waitcnt vmcnt(8) lgkmcnt(0)
	s_barrier
	s_setprio 1
	v_mfma_f32_16x16x32_bf16 v[62:65], v[146:149], v[172:175], v[62:65]
	v_mfma_f32_16x16x32_bf16 v[58:61], v[164:167], v[172:175], v[58:61]
	v_mfma_f32_16x16x32_bf16 v[50:53], v[146:149], v[180:183], v[50:53]
	v_mfma_f32_16x16x32_bf16 v[42:45], v[164:167], v[180:183], v[42:45]
	v_mfma_f32_16x16x32_bf16 v[34:37], v[146:149], v[204:207], v[34:37]
	v_mfma_f32_16x16x32_bf16 v[26:29], v[164:167], v[204:207], v[26:29]
	v_mfma_f32_16x16x32_bf16 v[18:21], v[146:149], v[212:215], v[18:21]
	v_mfma_f32_16x16x32_bf16 v[10:13], v[164:167], v[212:215], v[10:13]
	v_mfma_f32_16x16x32_bf16 v[62:65], v[150:153], v[176:179], v[62:65]
	v_mfma_f32_16x16x32_bf16 v[58:61], v[168:171], v[176:179], v[58:61]
	v_mfma_f32_16x16x32_bf16 v[50:53], v[150:153], v[184:187], v[50:53]
	v_mfma_f32_16x16x32_bf16 v[42:45], v[168:171], v[184:187], v[42:45]
	v_mfma_f32_16x16x32_bf16 v[34:37], v[150:153], v[208:211], v[34:37]
	v_mfma_f32_16x16x32_bf16 v[26:29], v[168:171], v[208:211], v[26:29]
	v_mfma_f32_16x16x32_bf16 v[18:21], v[150:153], v[216:219], v[18:21]
	v_mfma_f32_16x16x32_bf16 v[10:13], v[168:171], v[216:219], v[10:13]
	v_mfma_f32_16x16x32_bf16 v[54:57], v[220:223], v[172:175], v[54:57]
	v_mfma_f32_16x16x32_bf16 v[46:49], v[228:231], v[172:175], v[46:49]
	v_mfma_f32_16x16x32_bf16 v[38:41], v[220:223], v[180:183], v[38:41]
	v_mfma_f32_16x16x32_bf16 v[30:33], v[228:231], v[180:183], v[30:33]
	v_mfma_f32_16x16x32_bf16 v[22:25], v[220:223], v[204:207], v[22:25]
	v_mfma_f32_16x16x32_bf16 v[14:17], v[228:231], v[204:207], v[14:17]
	v_mfma_f32_16x16x32_bf16 v[6:9], v[220:223], v[212:215], v[6:9]
	v_mfma_f32_16x16x32_bf16 v[2:5], v[228:231], v[212:215], v[2:5]
	v_mfma_f32_16x16x32_bf16 v[54:57], v[224:227], v[176:179], v[54:57]
	v_mfma_f32_16x16x32_bf16 v[46:49], v[232:235], v[176:179], v[46:49]
	v_mfma_f32_16x16x32_bf16 v[38:41], v[224:227], v[184:187], v[38:41]
	v_mfma_f32_16x16x32_bf16 v[30:33], v[232:235], v[184:187], v[30:33]
	v_mfma_f32_16x16x32_bf16 v[22:25], v[224:227], v[208:211], v[22:25]
	v_mfma_f32_16x16x32_bf16 v[14:17], v[232:235], v[208:211], v[14:17]
	v_mfma_f32_16x16x32_bf16 v[6:9], v[224:227], v[216:219], v[6:9]
	v_mfma_f32_16x16x32_bf16 v[2:5], v[232:235], v[216:219], v[2:5]
	s_setprio 0
	s_add_i32 s40, s40, 2
	s_add_u32 s14, s14, 0x100
	s_addc_u32 s15, s15, 0
	s_add_u32 s36, s36, 0x100
	s_addc_u32 s37, s37, 0
	s_cmp_gt_u32 s40, 13
	s_barrier
.LBB0_1156:
	s_add_u32 s16, s14, 0xfffc0080
	s_addc_u32 s17, s15, -1
	s_add_i32 s41, 0, 0x10000
	v_add_u32_e32 v249, s41, v154
	ds_read_b128 v[146:149], v249
	ds_read_b128 v[150:153], v249 offset:1024
	ds_read_b128 v[164:167], v249 offset:2048
	ds_read_b128 v[168:171], v249 offset:3072
	s_cmp_eq_u32 s40, 12
	s_cselect_b32 s19, s5, s17
	s_cselect_b32 s18, s34, s16
	s_cselect_b32 s17, s3, s37
	s_cselect_b32 s16, s35, s36
	s_add_i32 s44, 0, 0x14000
	ds_read_b128 v[220:223], v249 offset:16384
	ds_read_b128 v[224:227], v249 offset:17408
	ds_read_b128 v[228:231], v249 offset:18432
	ds_read_b128 v[232:235], v249 offset:19456
	s_add_i32 m0, s9, 0xc000
	ds_read_b128 v[172:175], v163
	ds_read_b128 v[176:179], v163 offset:1024
	ds_read_b128 v[180:183], v163 offset:2048
	ds_read_b128 v[184:187], v163 offset:3072
	ds_read_b128 v[204:207], v163 offset:4096
	ds_read_b128 v[208:211], v163 offset:5120
	ds_read_b128 v[212:215], v163 offset:6144
	ds_read_b128 v[216:219], v163 offset:7168
	global_load_lds_dwordx4 v138, s[14:15]
	s_add_i32 m0, s9, 0xe000
	s_nop 0
	global_load_lds_dwordx4 v140, s[14:15]
	s_waitcnt vmcnt(8) lgkmcnt(0)
	s_barrier
	s_setprio 1
	v_mfma_f32_16x16x32_bf16 v[126:129], v[146:149], v[172:175], v[126:129]
	v_mfma_f32_16x16x32_bf16 v[122:125], v[164:167], v[172:175], v[122:125]
	v_mfma_f32_16x16x32_bf16 v[114:117], v[146:149], v[180:183], v[114:117]
	v_mfma_f32_16x16x32_bf16 v[106:109], v[164:167], v[180:183], v[106:109]
	v_mfma_f32_16x16x32_bf16 v[98:101], v[146:149], v[204:207], v[98:101]
	v_mfma_f32_16x16x32_bf16 v[90:93], v[164:167], v[204:207], v[90:93]
	v_mfma_f32_16x16x32_bf16 v[82:85], v[146:149], v[212:215], v[82:85]
	v_mfma_f32_16x16x32_bf16 v[74:77], v[164:167], v[212:215], v[74:77]
	v_mfma_f32_16x16x32_bf16 v[126:129], v[150:153], v[176:179], v[126:129]
	v_mfma_f32_16x16x32_bf16 v[122:125], v[168:171], v[176:179], v[122:125]
	v_mfma_f32_16x16x32_bf16 v[114:117], v[150:153], v[184:187], v[114:117]
	v_mfma_f32_16x16x32_bf16 v[106:109], v[168:171], v[184:187], v[106:109]
	v_mfma_f32_16x16x32_bf16 v[98:101], v[150:153], v[208:211], v[98:101]
	v_mfma_f32_16x16x32_bf16 v[90:93], v[168:171], v[208:211], v[90:93]
	v_mfma_f32_16x16x32_bf16 v[82:85], v[150:153], v[216:219], v[82:85]
	v_mfma_f32_16x16x32_bf16 v[74:77], v[168:171], v[216:219], v[74:77]
	v_mfma_f32_16x16x32_bf16 v[118:121], v[220:223], v[172:175], v[118:121]
	v_mfma_f32_16x16x32_bf16 v[110:113], v[228:231], v[172:175], v[110:113]
	v_mfma_f32_16x16x32_bf16 v[102:105], v[220:223], v[180:183], v[102:105]
	v_mfma_f32_16x16x32_bf16 v[94:97], v[228:231], v[180:183], v[94:97]
	v_mfma_f32_16x16x32_bf16 v[86:89], v[220:223], v[204:207], v[86:89]
	v_mfma_f32_16x16x32_bf16 v[78:81], v[228:231], v[204:207], v[78:81]
	v_mfma_f32_16x16x32_bf16 v[70:73], v[220:223], v[212:215], v[70:73]
	v_mfma_f32_16x16x32_bf16 v[66:69], v[228:231], v[212:215], v[66:69]
	v_mfma_f32_16x16x32_bf16 v[118:121], v[224:227], v[176:179], v[118:121]
	v_mfma_f32_16x16x32_bf16 v[110:113], v[232:235], v[176:179], v[110:113]
	v_mfma_f32_16x16x32_bf16 v[102:105], v[224:227], v[184:187], v[102:105]
	v_mfma_f32_16x16x32_bf16 v[94:97], v[232:235], v[184:187], v[94:97]
	v_mfma_f32_16x16x32_bf16 v[86:89], v[224:227], v[208:211], v[86:89]
	v_mfma_f32_16x16x32_bf16 v[78:81], v[232:235], v[208:211], v[78:81]
	v_mfma_f32_16x16x32_bf16 v[70:73], v[224:227], v[216:219], v[70:73]
	v_mfma_f32_16x16x32_bf16 v[66:69], v[232:235], v[216:219], v[66:69]
	s_setprio 0
	s_barrier
	ds_read_b128 v[172:175], v163 offset:16384
	ds_read_b128 v[176:179], v163 offset:17408
	ds_read_b128 v[180:183], v163 offset:18432
	ds_read_b128 v[184:187], v163 offset:19456
	ds_read_b128 v[204:207], v163 offset:20480
	ds_read_b128 v[208:211], v163 offset:21504
	ds_read_b128 v[212:215], v163 offset:22528
	ds_read_b128 v[216:219], v163 offset:23552
	s_add_i32 s41, s41, s25
	s_mov_b32 m0, s41
	s_nop 0
	global_load_lds_dwordx4 v132, s[16:17]
	s_add_i32 m0, s41, 0x2000
	s_nop 0
	global_load_lds_dwordx4 v136, s[16:17]
	s_mov_b32 m0, s9
	s_add_u32 s98, s18, 0x80
	s_addc_u32 s99, s19, 0
	global_load_lds_dwordx4 v130, s[18:19]
	s_mov_b32 m0, s26
	s_nop 0
	global_load_lds_dwordx4 v134, s[18:19]
	s_add_u32 s42, s16, 0x40000
	s_addc_u32 s43, s17, 0
	s_add_i32 s41, s44, s25
	s_mov_b32 m0, s41
	s_nop 0
	global_load_lds_dwordx4 v132, s[42:43]
	s_add_i32 m0, s41, 0x2000
	s_nop 0
	global_load_lds_dwordx4 v136, s[42:43]
	s_waitcnt vmcnt(8) lgkmcnt(0)
	s_barrier
	s_setprio 1
	v_mfma_f32_16x16x32_bf16 v[62:65], v[146:149], v[172:175], v[62:65]
	v_mfma_f32_16x16x32_bf16 v[58:61], v[164:167], v[172:175], v[58:61]
	v_mfma_f32_16x16x32_bf16 v[50:53], v[146:149], v[180:183], v[50:53]
	v_mfma_f32_16x16x32_bf16 v[42:45], v[164:167], v[180:183], v[42:45]
	v_mfma_f32_16x16x32_bf16 v[34:37], v[146:149], v[204:207], v[34:37]
	v_mfma_f32_16x16x32_bf16 v[26:29], v[164:167], v[204:207], v[26:29]
	v_mfma_f32_16x16x32_bf16 v[18:21], v[146:149], v[212:215], v[18:21]
	v_mfma_f32_16x16x32_bf16 v[10:13], v[164:167], v[212:215], v[10:13]
	v_mfma_f32_16x16x32_bf16 v[62:65], v[150:153], v[176:179], v[62:65]
	v_mfma_f32_16x16x32_bf16 v[58:61], v[168:171], v[176:179], v[58:61]
	v_mfma_f32_16x16x32_bf16 v[50:53], v[150:153], v[184:187], v[50:53]
	v_mfma_f32_16x16x32_bf16 v[42:45], v[168:171], v[184:187], v[42:45]
	v_mfma_f32_16x16x32_bf16 v[34:37], v[150:153], v[208:211], v[34:37]
	v_mfma_f32_16x16x32_bf16 v[26:29], v[168:171], v[208:211], v[26:29]
	v_mfma_f32_16x16x32_bf16 v[18:21], v[150:153], v[216:219], v[18:21]
	v_mfma_f32_16x16x32_bf16 v[10:13], v[168:171], v[216:219], v[10:13]
	v_mfma_f32_16x16x32_bf16 v[54:57], v[220:223], v[172:175], v[54:57]
	v_mfma_f32_16x16x32_bf16 v[46:49], v[228:231], v[172:175], v[46:49]
	v_mfma_f32_16x16x32_bf16 v[38:41], v[220:223], v[180:183], v[38:41]
	v_mfma_f32_16x16x32_bf16 v[30:33], v[228:231], v[180:183], v[30:33]
	v_mfma_f32_16x16x32_bf16 v[22:25], v[220:223], v[204:207], v[22:25]
	v_mfma_f32_16x16x32_bf16 v[14:17], v[228:231], v[204:207], v[14:17]
	v_mfma_f32_16x16x32_bf16 v[6:9], v[220:223], v[212:215], v[6:9]
	v_mfma_f32_16x16x32_bf16 v[2:5], v[228:231], v[212:215], v[2:5]
	v_mfma_f32_16x16x32_bf16 v[54:57], v[224:227], v[176:179], v[54:57]
	v_mfma_f32_16x16x32_bf16 v[46:49], v[232:235], v[176:179], v[46:49]
	v_mfma_f32_16x16x32_bf16 v[38:41], v[224:227], v[184:187], v[38:41]
	v_mfma_f32_16x16x32_bf16 v[30:33], v[232:235], v[184:187], v[30:33]
	v_mfma_f32_16x16x32_bf16 v[22:25], v[224:227], v[208:211], v[22:25]
	v_mfma_f32_16x16x32_bf16 v[14:17], v[232:235], v[208:211], v[14:17]
	v_mfma_f32_16x16x32_bf16 v[6:9], v[224:227], v[216:219], v[6:9]
	v_mfma_f32_16x16x32_bf16 v[2:5], v[232:235], v[216:219], v[2:5]
	s_setprio 0
	s_barrier
	s_add_i32 s41, 0, 0x18000
	ds_read_b128 v[146:149], v249 offset:32768
	ds_read_b128 v[150:153], v249 offset:33792
	ds_read_b128 v[164:167], v249 offset:34816
	ds_read_b128 v[168:171], v249 offset:35840
	s_add_u32 s18, s18, 0x40000
	s_addc_u32 s19, s19, 0
	s_mov_b32 m0, s27
	ds_read_b128 v[172:175], v163 offset:32768
	ds_read_b128 v[176:179], v163 offset:33792
	ds_read_b128 v[180:183], v163 offset:34816
	ds_read_b128 v[184:187], v163 offset:35840
	ds_read_b128 v[204:207], v163 offset:36864
	ds_read_b128 v[208:211], v163 offset:37888
	ds_read_b128 v[212:215], v163 offset:38912
	ds_read_b128 v[216:219], v163 offset:39936
	global_load_lds_dwordx4 v130, s[18:19]
	s_mov_b32 m0, s28
	s_nop 0
	global_load_lds_dwordx4 v134, s[18:19]
	s_add_i32 s18, 0, 0x1c000
	ds_read_b128 v[220:223], v249 offset:49152
	ds_read_b128 v[224:227], v249 offset:50176
	ds_read_b128 v[228:231], v249 offset:51200
	ds_read_b128 v[232:235], v249 offset:52224
	s_waitcnt vmcnt(8) lgkmcnt(0)
	s_barrier
	s_setprio 1
	v_mfma_f32_16x16x32_bf16 v[126:129], v[146:149], v[172:175], v[126:129]
	v_mfma_f32_16x16x32_bf16 v[122:125], v[164:167], v[172:175], v[122:125]
	v_mfma_f32_16x16x32_bf16 v[114:117], v[146:149], v[180:183], v[114:117]
	v_mfma_f32_16x16x32_bf16 v[106:109], v[164:167], v[180:183], v[106:109]
	v_mfma_f32_16x16x32_bf16 v[98:101], v[146:149], v[204:207], v[98:101]
	v_mfma_f32_16x16x32_bf16 v[90:93], v[164:167], v[204:207], v[90:93]
	v_mfma_f32_16x16x32_bf16 v[82:85], v[146:149], v[212:215], v[82:85]
	v_mfma_f32_16x16x32_bf16 v[74:77], v[164:167], v[212:215], v[74:77]
	v_mfma_f32_16x16x32_bf16 v[126:129], v[150:153], v[176:179], v[126:129]
	v_mfma_f32_16x16x32_bf16 v[122:125], v[168:171], v[176:179], v[122:125]
	v_mfma_f32_16x16x32_bf16 v[114:117], v[150:153], v[184:187], v[114:117]
	v_mfma_f32_16x16x32_bf16 v[106:109], v[168:171], v[184:187], v[106:109]
	v_mfma_f32_16x16x32_bf16 v[98:101], v[150:153], v[208:211], v[98:101]
	v_mfma_f32_16x16x32_bf16 v[90:93], v[168:171], v[208:211], v[90:93]
	v_mfma_f32_16x16x32_bf16 v[82:85], v[150:153], v[216:219], v[82:85]
	v_mfma_f32_16x16x32_bf16 v[74:77], v[168:171], v[216:219], v[74:77]
	v_mfma_f32_16x16x32_bf16 v[118:121], v[220:223], v[172:175], v[118:121]
	v_mfma_f32_16x16x32_bf16 v[110:113], v[228:231], v[172:175], v[110:113]
	v_mfma_f32_16x16x32_bf16 v[102:105], v[220:223], v[180:183], v[102:105]
	v_mfma_f32_16x16x32_bf16 v[94:97], v[228:231], v[180:183], v[94:97]
	v_mfma_f32_16x16x32_bf16 v[86:89], v[220:223], v[204:207], v[86:89]
	v_mfma_f32_16x16x32_bf16 v[78:81], v[228:231], v[204:207], v[78:81]
	v_mfma_f32_16x16x32_bf16 v[70:73], v[220:223], v[212:215], v[70:73]
	v_mfma_f32_16x16x32_bf16 v[66:69], v[228:231], v[212:215], v[66:69]
	v_mfma_f32_16x16x32_bf16 v[118:121], v[224:227], v[176:179], v[118:121]
	v_mfma_f32_16x16x32_bf16 v[110:113], v[232:235], v[176:179], v[110:113]
	v_mfma_f32_16x16x32_bf16 v[102:105], v[224:227], v[184:187], v[102:105]
	v_mfma_f32_16x16x32_bf16 v[94:97], v[232:235], v[184:187], v[94:97]
	v_mfma_f32_16x16x32_bf16 v[86:89], v[224:227], v[208:211], v[86:89]
	v_mfma_f32_16x16x32_bf16 v[78:81], v[232:235], v[208:211], v[78:81]
	v_mfma_f32_16x16x32_bf16 v[70:73], v[224:227], v[216:219], v[70:73]
	v_mfma_f32_16x16x32_bf16 v[66:69], v[232:235], v[216:219], v[66:69]
	s_setprio 0
	s_barrier
	ds_read_b128 v[172:175], v163 offset:49152
	ds_read_b128 v[176:179], v163 offset:50176
	ds_read_b128 v[180:183], v163 offset:51200
	ds_read_b128 v[184:187], v163 offset:52224
	ds_read_b128 v[204:207], v163 offset:53248
	ds_read_b128 v[208:211], v163 offset:54272
	ds_read_b128 v[212:215], v163 offset:55296
	ds_read_b128 v[216:219], v163 offset:56320
	s_add_i32 s19, s41, s25
	s_mov_b32 m0, s19
	s_add_u32 vcc_lo, s16, 0x80
	s_addc_u32 vcc_hi, s17, 0
	global_load_lds_dwordx4 v132, vcc
	s_add_i32 m0, s19, 0x2000
	s_nop 0
	global_load_lds_dwordx4 v136, vcc
	s_mov_b32 m0, s29
	s_nop 0
	global_load_lds_dwordx4 v130, s[98:99]
	s_mov_b32 m0, s30
	s_nop 0
	global_load_lds_dwordx4 v134, s[98:99]
	s_add_u32 s16, s16, 0x40080
	s_addc_u32 s17, s17, 0
	s_add_i32 s18, s18, s25
	s_mov_b32 m0, s18
	s_nop 0
	global_load_lds_dwordx4 v132, s[16:17]
	s_add_i32 m0, s18, 0x2000
	s_nop 0
	global_load_lds_dwordx4 v136, s[16:17]
	s_waitcnt vmcnt(8) lgkmcnt(0)
	s_barrier
	s_setprio 1
	v_mfma_f32_16x16x32_bf16 v[62:65], v[146:149], v[172:175], v[62:65]
	v_mfma_f32_16x16x32_bf16 v[58:61], v[164:167], v[172:175], v[58:61]
	v_mfma_f32_16x16x32_bf16 v[50:53], v[146:149], v[180:183], v[50:53]
	v_mfma_f32_16x16x32_bf16 v[42:45], v[164:167], v[180:183], v[42:45]
	v_mfma_f32_16x16x32_bf16 v[34:37], v[146:149], v[204:207], v[34:37]
	v_mfma_f32_16x16x32_bf16 v[26:29], v[164:167], v[204:207], v[26:29]
	v_mfma_f32_16x16x32_bf16 v[18:21], v[146:149], v[212:215], v[18:21]
	v_mfma_f32_16x16x32_bf16 v[10:13], v[164:167], v[212:215], v[10:13]
	v_mfma_f32_16x16x32_bf16 v[62:65], v[150:153], v[176:179], v[62:65]
	v_mfma_f32_16x16x32_bf16 v[58:61], v[168:171], v[176:179], v[58:61]
	v_mfma_f32_16x16x32_bf16 v[50:53], v[150:153], v[184:187], v[50:53]
	v_mfma_f32_16x16x32_bf16 v[42:45], v[168:171], v[184:187], v[42:45]
	v_mfma_f32_16x16x32_bf16 v[34:37], v[150:153], v[208:211], v[34:37]
	v_mfma_f32_16x16x32_bf16 v[26:29], v[168:171], v[208:211], v[26:29]
	v_mfma_f32_16x16x32_bf16 v[18:21], v[150:153], v[216:219], v[18:21]
	v_mfma_f32_16x16x32_bf16 v[10:13], v[168:171], v[216:219], v[10:13]
	v_mfma_f32_16x16x32_bf16 v[54:57], v[220:223], v[172:175], v[54:57]
	v_mfma_f32_16x16x32_bf16 v[46:49], v[228:231], v[172:175], v[46:49]
	v_mfma_f32_16x16x32_bf16 v[38:41], v[220:223], v[180:183], v[38:41]
	v_mfma_f32_16x16x32_bf16 v[30:33], v[228:231], v[180:183], v[30:33]
	v_mfma_f32_16x16x32_bf16 v[22:25], v[220:223], v[204:207], v[22:25]
	v_mfma_f32_16x16x32_bf16 v[14:17], v[228:231], v[204:207], v[14:17]
	v_mfma_f32_16x16x32_bf16 v[6:9], v[220:223], v[212:215], v[6:9]
	v_mfma_f32_16x16x32_bf16 v[2:5], v[228:231], v[212:215], v[2:5]
	v_mfma_f32_16x16x32_bf16 v[54:57], v[224:227], v[176:179], v[54:57]
	v_mfma_f32_16x16x32_bf16 v[46:49], v[232:235], v[176:179], v[46:49]
	v_mfma_f32_16x16x32_bf16 v[38:41], v[224:227], v[184:187], v[38:41]
	v_mfma_f32_16x16x32_bf16 v[30:33], v[232:235], v[184:187], v[30:33]
	v_mfma_f32_16x16x32_bf16 v[22:25], v[224:227], v[208:211], v[22:25]
	v_mfma_f32_16x16x32_bf16 v[14:17], v[232:235], v[208:211], v[14:17]
	v_mfma_f32_16x16x32_bf16 v[6:9], v[224:227], v[216:219], v[6:9]
	v_mfma_f32_16x16x32_bf16 v[2:5], v[232:235], v[216:219], v[2:5]
	s_setprio 0
	s_add_i32 s40, s40, 2
	s_add_u32 s14, s14, 0x100
	s_addc_u32 s15, s15, 0
	s_add_u32 s36, s36, 0x100
	s_addc_u32 s37, s37, 0
	s_cmp_gt_u32 s40, 13
	s_barrier
	s_cbranch_scc0 .LBB0_1156
	s_mov_b64 s[14:15], -1
	s_cmp_gt_i32 s6, 5
	v_lshl_add_u32 v143, s7, 8, v145
	s_cbranch_scc0 .LBB0_1175
	v_lshl_add_u32 v144, v143, 2, 0
	v_add_u32_e32 v164, 0x20040, v144
	ds_read_b32 v144, v164
	s_cmp_gt_u32 s6, 7
	s_cselect_b64 s[14:15], -1, 0
	s_cmp_lt_u32 s6, 8
	s_waitcnt lgkmcnt(0)
	v_pk_mul_f32 v[146:147], v[122:123], v[144:145] op_sel_hi:[1,0]
	v_pk_mul_f32 v[152:153], v[124:125], v[144:145] op_sel_hi:[1,0]
	v_pk_mul_f32 v[148:149], v[110:111], v[144:145] op_sel_hi:[1,0]
	v_pk_mul_f32 v[150:151], v[112:113], v[144:145] op_sel_hi:[1,0]
	s_cbranch_scc1 .LBB0_1160
	v_mul_f32_e32 v146, 0xbfb8aa3b, v146
	v_mul_f32_e32 v147, 0xbfb8aa3b, v147
	v_mul_f32_e32 v152, 0xbfb8aa3b, v152
	v_mul_f32_e32 v153, 0xbfb8aa3b, v153
	v_mul_f32_e32 v148, 0xbfb8aa3b, v148
	v_mul_f32_e32 v149, 0xbfb8aa3b, v149
	v_mul_f32_e32 v150, 0xbfb8aa3b, v150
	v_mul_f32_e32 v151, 0xbfb8aa3b, v151
	v_exp_f32_e32 v146, v146
	v_exp_f32_e32 v147, v147
	v_exp_f32_e32 v152, v152
	v_exp_f32_e32 v153, v153
	v_exp_f32_e32 v148, v148
	v_exp_f32_e32 v149, v149
	v_exp_f32_e32 v150, v150
	v_exp_f32_e32 v151, v151
	v_add_f32_e32 v146, 1.0, v146
	v_add_f32_e32 v147, 1.0, v147
	v_add_f32_e32 v152, 1.0, v152
	v_add_f32_e32 v153, 1.0, v153
	v_add_f32_e32 v148, 1.0, v148
	v_add_f32_e32 v149, 1.0, v149
	v_add_f32_e32 v150, 1.0, v150
	v_add_f32_e32 v151, 1.0, v151
	v_rcp_f32_e32 v146, v146
	v_rcp_f32_e32 v147, v147
	v_rcp_f32_e32 v152, v152
	v_rcp_f32_e32 v153, v153
	v_rcp_f32_e32 v148, v148
	v_rcp_f32_e32 v149, v149
	v_rcp_f32_e32 v150, v150
	v_rcp_f32_e32 v151, v151
